# MFMA order b,n,m with zig-zag k (adjacent accumulators share an operand register) + the other edits
# baseline (speedup 1.0000x reference)
; #define PG8_STAGE(bufoff, gbase, voff) do { _Pragma("unroll") for (int _i = 0; _i < 2; ++_i) \
;         __builtin_amdgcn_global_load_lds((const unsigned*)((const char*)(gbase) + (voff)[_i]), (PG8_LAS unsigned*)(lds + (bufoff) + ldsw + _i * 8192), 16, 0, 0); } while (0)
; #define PG8_LDA(dst, b, h) do { _Pragma("unroll") for (int m = 0; m < 4; ++m) _Pragma("unroll") for (int k = 0; k < 2; ++k) dst[m][k] = *(const PG8_LAS bf16x8*)(lds + PG8_SA(b, h) + aoff + m * 2048 + k * 1024); } while (0)
; #define PG8_LDB(dst, b, h) do { _Pragma("unroll") for (int n = 0; n < 2; ++n) _Pragma("unroll") for (int k = 0; k < 2; ++k) dst[n][k] = *(const PG8_LAS bf16x8*)(lds + PG8_SB(b, h) + boff + n * 2048 + k * 1024); } while (0)
; #define PG8_MMA(ai, bj, At, Bt) do { __builtin_amdgcn_s_setprio(1); _Pragma("unroll") for (int m = 0; m < 4; ++m) _Pragma("unroll") for (int n = 0; n < 2; ++n) _Pragma("unroll") for (int k = 0; k < 2; ++k) \
;         acc[ai][bj][m][n] = __builtin_amdgcn_mfma_f32_16x16x32_bf16(Bt[n][k], At[m][k], acc[ai][bj][m][n], 0, 0, 0); __builtin_amdgcn_s_setprio(0); } while (0)
; #define PG8_WAIT_V(n) asm volatile("s_waitcnt vmcnt(" #n ")" ::: "memory")
; #define PG8_WAIT_L(n) asm volatile("s_waitcnt lgkmcnt(" #n ")" ::: "memory")
; template <class Epi, class Sched, bool ALIGN_EPI = false, bool SP2 = false>
; __device__ __forceinline__ void gemm_phase(PG8_LAS unsigned char* lds, const Gemm g, const Sched& S, const Epi& E) {
;     ...
;             const bool last = (t == nt - 2);
;             const char* a1 = cA + (size_t)(t + 1) * kstep;
;             const char* a2 = last ? nA : cA + (size_t)(t + 2) * kstep; const char* b2 = last ? nB : cB + (size_t)(t + 2) * kstep;
;             const char* a3 = a2 + kstep; const char* b3 = b2 + kstep;
;             if (last && has_next) S.a_ready(nxt);
;             if constexpr (SP2) {
;             PG8_LDB(B0, 0, 0); PG8_LDB(B1, 0, 1); PG8_SCHED; PG8_LDA(At, 0, 0); PG8_STAGE(PG8_SA(1, 1), a1 + hstep, voffA);
;             PG8_WAIT_V(8); PG8_WAIT_L(0); PG8_BAR; PG8_MMA(0, 0, At, B0); PG8_MMA(0, 1, At, B1); PG8_BAR; PG8_SCHED;
;             PG8_LDA(At, 0, 1); PG8_STAGE(PG8_SB(0, 0), b2, voffB); PG8_STAGE(PG8_SB(0, 1), b2 + hstep, voffB); PG8_STAGE(PG8_SA(0, 0), a2, voffA);
;             PG8_WAIT_V(8); PG8_WAIT_L(0); PG8_BAR; PG8_MMA(1, 0, At, B0); PG8_MMA(1, 1, At, B1); PG8_BAR; PG8_SCHED;
.LBB0_132:
	s_add_u32 s18, s46, 0xfffc0080
	s_addc_u32 s38, s47, -1
	s_add_i32 s39, 0, 0x10000
	s_cmp_eq_u32 s85, 12
	s_cselect_b32 s81, s33, s38
	s_cselect_b32 s80, s73, s18
	v_add_u32_e32 v0, s39, v176
	s_cselect_b32 s45, s75, s84
	s_cselect_b32 s44, s82, s83
	s_add_i32 s18, 0, 0x14000
	ds_read_b128 v[144:147], v0
	ds_read_b128 v[148:151], v0 offset:1024
	ds_read_b128 v[152:155], v0 offset:2048
	ds_read_b128 v[156:159], v0 offset:3072
	v_add_u32_e32 v0, s18, v176
	ds_read_b128 v[160:163], v0
	ds_read_b128 v[164:167], v0 offset:1024
	ds_read_b128 v[168:171], v0 offset:2048
	ds_read_b128 v[172:175], v0 offset:3072
	v_lshl_add_u64 v[218:219], s[46:47], 0, v[140:141]
	s_add_i32 m0, s92, 0xc000
	ds_read_b128 v[180:183], v178
	ds_read_b128 v[184:187], v178 offset:1024
	ds_read_b128 v[188:191], v178 offset:2048
	ds_read_b128 v[192:195], v178 offset:3072
	ds_read_b128 v[202:205], v178 offset:4096
	ds_read_b128 v[206:209], v178 offset:5120
	ds_read_b128 v[210:213], v178 offset:6144
	ds_read_b128 v[214:217], v178 offset:7168
	global_load_lds_dwordx4 v[218:219], off
	v_lshl_add_u64 v[218:219], s[46:47], 0, v[142:143]
	s_add_i32 m0, s92, 0xe000
	s_nop 0
	global_load_lds_dwordx4 v[218:219], off
	s_waitcnt vmcnt(8)
	s_waitcnt lgkmcnt(0)
	s_barrier
	s_setprio 1
	v_mfma_f32_16x16x32_bf16 v[118:121], v[144:147], v[180:183], v[118:121]
	v_mfma_f32_16x16x32_bf16 v[118:121], v[148:151], v[184:187], v[118:121]
	v_mfma_f32_16x16x32_bf16 v[102:105], v[148:151], v[192:195], v[102:105]
	v_mfma_f32_16x16x32_bf16 v[102:105], v[144:147], v[188:191], v[102:105]
	v_mfma_f32_16x16x32_bf16 v[86:89], v[144:147], v[202:205], v[86:89]
	v_mfma_f32_16x16x32_bf16 v[86:89], v[148:151], v[206:209], v[86:89]
	v_mfma_f32_16x16x32_bf16 v[70:73], v[148:151], v[214:217], v[70:73]
	v_mfma_f32_16x16x32_bf16 v[70:73], v[144:147], v[210:213], v[70:73]
	v_mfma_f32_16x16x32_bf16 v[114:117], v[152:155], v[180:183], v[114:117]
	v_mfma_f32_16x16x32_bf16 v[114:117], v[156:159], v[184:187], v[114:117]
	v_mfma_f32_16x16x32_bf16 v[98:101], v[156:159], v[192:195], v[98:101]
	v_mfma_f32_16x16x32_bf16 v[98:101], v[152:155], v[188:191], v[98:101]
	v_mfma_f32_16x16x32_bf16 v[82:85], v[152:155], v[202:205], v[82:85]
	v_mfma_f32_16x16x32_bf16 v[82:85], v[156:159], v[206:209], v[82:85]
	v_mfma_f32_16x16x32_bf16 v[66:69], v[156:159], v[214:217], v[66:69]
	v_mfma_f32_16x16x32_bf16 v[66:69], v[152:155], v[210:213], v[66:69]
	v_mfma_f32_16x16x32_bf16 v[126:129], v[160:163], v[180:183], v[126:129]
	v_mfma_f32_16x16x32_bf16 v[126:129], v[164:167], v[184:187], v[126:129]
	v_mfma_f32_16x16x32_bf16 v[110:113], v[164:167], v[192:195], v[110:113]
	v_mfma_f32_16x16x32_bf16 v[110:113], v[160:163], v[188:191], v[110:113]
	v_mfma_f32_16x16x32_bf16 v[94:97], v[160:163], v[202:205], v[94:97]
	v_mfma_f32_16x16x32_bf16 v[94:97], v[164:167], v[206:209], v[94:97]
	v_mfma_f32_16x16x32_bf16 v[78:81], v[164:167], v[214:217], v[78:81]
	v_mfma_f32_16x16x32_bf16 v[78:81], v[160:163], v[210:213], v[78:81]
	v_mfma_f32_16x16x32_bf16 v[122:125], v[168:171], v[180:183], v[122:125]
	v_mfma_f32_16x16x32_bf16 v[122:125], v[172:175], v[184:187], v[122:125]
	v_mfma_f32_16x16x32_bf16 v[106:109], v[172:175], v[192:195], v[106:109]
	v_mfma_f32_16x16x32_bf16 v[106:109], v[168:171], v[188:191], v[106:109]
	v_mfma_f32_16x16x32_bf16 v[90:93], v[168:171], v[202:205], v[90:93]
	v_mfma_f32_16x16x32_bf16 v[90:93], v[172:175], v[206:209], v[90:93]
	v_mfma_f32_16x16x32_bf16 v[74:77], v[172:175], v[214:217], v[74:77]
	v_mfma_f32_16x16x32_bf16 v[74:77], v[168:171], v[210:213], v[74:77]
	s_setprio 0
	s_barrier
	s_add_i32 s38, s39, s91
	v_lshl_add_u64 v[218:219], s[44:45], 0, v[134:135]
	s_mov_b32 m0, s38
	ds_read_b128 v[180:183], v178 offset:16384
	ds_read_b128 v[184:187], v178 offset:17408
	ds_read_b128 v[188:191], v178 offset:18432
	ds_read_b128 v[192:195], v178 offset:19456
	ds_read_b128 v[202:205], v178 offset:20480
	ds_read_b128 v[206:209], v178 offset:21504
	ds_read_b128 v[210:213], v178 offset:22528
	ds_read_b128 v[214:217], v178 offset:23552
	global_load_lds_dwordx4 v[218:219], off
	s_add_i32 m0, s38, 0x2000
	s_add_u32 s38, s44, 0x40000
	v_lshl_add_u64 v[220:221], s[44:45], 0, v[130:131]
	s_addc_u32 s39, s45, 0
	s_add_i32 s18, s18, s91
	global_load_lds_dwordx4 v[220:221], off
	v_lshl_add_u64 v[222:223], s[38:39], 0, v[134:135]
	s_mov_b32 m0, s18
	v_lshl_add_u64 v[224:225], s[80:81], 0, v[132:133]
	global_load_lds_dwordx4 v[222:223], off
	v_lshl_add_u64 v[222:223], s[38:39], 0, v[130:131]
	s_add_i32 m0, s18, 0x2000
	s_nop 0
	global_load_lds_dwordx4 v[222:223], off
	v_lshl_add_u64 v[222:223], s[80:81], 0, v[136:137]
	s_mov_b32 m0, s92
	s_nop 0
	global_load_lds_dwordx4 v[222:223], off
	s_mov_b32 m0, s93
	s_nop 0
	global_load_lds_dwordx4 v[224:225], off
	s_waitcnt vmcnt(8)
	s_waitcnt lgkmcnt(0)
	s_barrier
; #define PG8_STAGE(bufoff, gbase, voff) do { _Pragma("unroll") for (int _i = 0; _i < 2; ++_i) \
;         __builtin_amdgcn_global_load_lds((const unsigned*)((const char*)(gbase) + (voff)[_i]), (PG8_LAS unsigned*)(lds + (bufoff) + ldsw + _i * 8192), 16, 0, 0); } while (0)
; #define PG8_LDA(dst, b, h) do { _Pragma("unroll") for (int m = 0; m < 4; ++m) _Pragma("unroll") for (int k = 0; k < 2; ++k) dst[m][k] = *(const PG8_LAS bf16x8*)(lds + PG8_SA(b, h) + aoff + m * 2048 + k * 1024); } while (0)
; #define PG8_LDB(dst, b, h) do { _Pragma("unroll") for (int n = 0; n < 2; ++n) _Pragma("unroll") for (int k = 0; k < 2; ++k) dst[n][k] = *(const PG8_LAS bf16x8*)(lds + PG8_SB(b, h) + boff + n * 2048 + k * 1024); } while (0)
; #define PG8_MMA(ai, bj, At, Bt) do { __builtin_amdgcn_s_setprio(1); _Pragma("unroll") for (int m = 0; m < 4; ++m) _Pragma("unroll") for (int n = 0; n < 2; ++n) _Pragma("unroll") for (int k = 0; k < 2; ++k) \
;         acc[ai][bj][m][n] = __builtin_amdgcn_mfma_f32_16x16x32_bf16(Bt[n][k], At[m][k], acc[ai][bj][m][n], 0, 0, 0); __builtin_amdgcn_s_setprio(0); } while (0)
; #define PG8_WAIT_V(n) asm volatile("s_waitcnt vmcnt(" #n ")" ::: "memory")
; #define PG8_WAIT_L(n) asm volatile("s_waitcnt lgkmcnt(" #n ")" ::: "memory")
; #define PG8_BAR __builtin_amdgcn_s_barrier()
; #define PG8_SCHED __builtin_amdgcn_sched_barrier(0)
; template <class Epi, class Sched, bool ALIGN_EPI = false, bool SP2 = false>
; __device__ __forceinline__ void gemm_phase(PG8_LAS unsigned char* lds, const Gemm g, const Sched& S, const Epi& E) {
;     ...
;             PG8_WAIT_V(8); PG8_WAIT_L(0); PG8_BAR; PG8_MMA(1, 0, At, B0); PG8_MMA(1, 1, At, B1); PG8_BAR; PG8_SCHED;
;             PG8_LDB(B0, 1, 0); PG8_LDB(B1, 1, 1); PG8_SCHED; PG8_LDA(At, 1, 0); PG8_STAGE(PG8_SA(0, 1), a2 + hstep, voffA);
;             PG8_WAIT_V(8); PG8_WAIT_L(0); PG8_BAR; PG8_MMA(0, 0, At, B0); PG8_MMA(0, 1, At, B1); PG8_BAR; PG8_SCHED;
	s_setprio 1
	v_mfma_f32_16x16x32_bf16 v[54:57], v[144:147], v[180:183], v[54:57]
	v_mfma_f32_16x16x32_bf16 v[54:57], v[148:151], v[184:187], v[54:57]
	v_mfma_f32_16x16x32_bf16 v[38:41], v[148:151], v[192:195], v[38:41]
	v_mfma_f32_16x16x32_bf16 v[38:41], v[144:147], v[188:191], v[38:41]
	v_mfma_f32_16x16x32_bf16 v[22:25], v[144:147], v[202:205], v[22:25]
	v_mfma_f32_16x16x32_bf16 v[22:25], v[148:151], v[206:209], v[22:25]
	v_mfma_f32_16x16x32_bf16 v[6:9], v[148:151], v[214:217], v[6:9]
	v_mfma_f32_16x16x32_bf16 v[6:9], v[144:147], v[210:213], v[6:9]
	v_mfma_f32_16x16x32_bf16 v[50:53], v[152:155], v[180:183], v[50:53]
	v_mfma_f32_16x16x32_bf16 v[50:53], v[156:159], v[184:187], v[50:53]
	v_mfma_f32_16x16x32_bf16 v[34:37], v[156:159], v[192:195], v[34:37]
	v_mfma_f32_16x16x32_bf16 v[34:37], v[152:155], v[188:191], v[34:37]
	v_mfma_f32_16x16x32_bf16 v[18:21], v[152:155], v[202:205], v[18:21]
	v_mfma_f32_16x16x32_bf16 v[18:21], v[156:159], v[206:209], v[18:21]
	v_mfma_f32_16x16x32_bf16 v[2:5], v[156:159], v[214:217], v[2:5]
	v_mfma_f32_16x16x32_bf16 v[2:5], v[152:155], v[210:213], v[2:5]
	v_mfma_f32_16x16x32_bf16 v[62:65], v[160:163], v[180:183], v[62:65]
	v_mfma_f32_16x16x32_bf16 v[62:65], v[164:167], v[184:187], v[62:65]
	v_mfma_f32_16x16x32_bf16 v[46:49], v[164:167], v[192:195], v[46:49]
	v_mfma_f32_16x16x32_bf16 v[46:49], v[160:163], v[188:191], v[46:49]
	v_mfma_f32_16x16x32_bf16 v[30:33], v[160:163], v[202:205], v[30:33]
	v_mfma_f32_16x16x32_bf16 v[30:33], v[164:167], v[206:209], v[30:33]
	v_mfma_f32_16x16x32_bf16 v[10:13], v[164:167], v[214:217], v[10:13]
	v_mfma_f32_16x16x32_bf16 v[10:13], v[160:163], v[210:213], v[10:13]
	v_mfma_f32_16x16x32_bf16 v[58:61], v[168:171], v[180:183], v[58:61]
	v_mfma_f32_16x16x32_bf16 v[58:61], v[172:175], v[184:187], v[58:61]
	v_mfma_f32_16x16x32_bf16 v[42:45], v[172:175], v[192:195], v[42:45]
	v_mfma_f32_16x16x32_bf16 v[42:45], v[168:171], v[188:191], v[42:45]
	v_mfma_f32_16x16x32_bf16 v[26:29], v[168:171], v[202:205], v[26:29]
	v_mfma_f32_16x16x32_bf16 v[26:29], v[172:175], v[206:209], v[26:29]
	v_mfma_f32_16x16x32_bf16 v[14:17], v[172:175], v[214:217], v[14:17]
	v_mfma_f32_16x16x32_bf16 v[14:17], v[168:171], v[210:213], v[14:17]
	s_setprio 0
	s_barrier
	s_add_i32 s18, 0, 0x18000
	v_add_u32_e32 v0, s18, v176
	s_add_i32 vcc_lo, 0, 0x1c000
	ds_read_b128 v[144:147], v0
	ds_read_b128 v[148:151], v0 offset:1024
	ds_read_b128 v[152:155], v0 offset:2048
	ds_read_b128 v[156:159], v0 offset:3072
	v_add_u32_e32 v0, vcc_lo, v176
	ds_read_b128 v[160:163], v0
	ds_read_b128 v[164:167], v0 offset:1024
	ds_read_b128 v[168:171], v0 offset:2048
	ds_read_b128 v[172:175], v0 offset:3072
	s_add_u32 s38, s80, 0x40000
	s_addc_u32 s39, s81, 0
	s_mov_b32 m0, s94
	v_lshl_add_u64 v[226:227], s[38:39], 0, v[136:137]
	ds_read_b128 v[180:183], v178 offset:32768
	ds_read_b128 v[184:187], v178 offset:33792
	ds_read_b128 v[188:191], v178 offset:34816
	ds_read_b128 v[192:195], v178 offset:35840
	ds_read_b128 v[202:205], v178 offset:36864
	ds_read_b128 v[206:209], v178 offset:37888
	ds_read_b128 v[210:213], v178 offset:38912
	ds_read_b128 v[214:217], v178 offset:39936
	global_load_lds_dwordx4 v[226:227], off
	v_lshl_add_u64 v[226:227], s[38:39], 0, v[132:133]
	s_mov_b32 m0, s95
	s_nop 0
	global_load_lds_dwordx4 v[226:227], off
	s_waitcnt vmcnt(8)
	s_waitcnt lgkmcnt(0)
	s_barrier
	s_setprio 1
	v_mfma_f32_16x16x32_bf16 v[118:121], v[144:147], v[180:183], v[118:121]
	v_mfma_f32_16x16x32_bf16 v[118:121], v[148:151], v[184:187], v[118:121]
	v_mfma_f32_16x16x32_bf16 v[102:105], v[148:151], v[192:195], v[102:105]
	v_mfma_f32_16x16x32_bf16 v[102:105], v[144:147], v[188:191], v[102:105]
	v_mfma_f32_16x16x32_bf16 v[86:89], v[144:147], v[202:205], v[86:89]
	v_mfma_f32_16x16x32_bf16 v[86:89], v[148:151], v[206:209], v[86:89]
	v_mfma_f32_16x16x32_bf16 v[70:73], v[148:151], v[214:217], v[70:73]
	v_mfma_f32_16x16x32_bf16 v[70:73], v[144:147], v[210:213], v[70:73]
	v_mfma_f32_16x16x32_bf16 v[114:117], v[152:155], v[180:183], v[114:117]
	v_mfma_f32_16x16x32_bf16 v[114:117], v[156:159], v[184:187], v[114:117]
	v_mfma_f32_16x16x32_bf16 v[98:101], v[156:159], v[192:195], v[98:101]
	v_mfma_f32_16x16x32_bf16 v[98:101], v[152:155], v[188:191], v[98:101]
	v_mfma_f32_16x16x32_bf16 v[82:85], v[152:155], v[202:205], v[82:85]
	v_mfma_f32_16x16x32_bf16 v[82:85], v[156:159], v[206:209], v[82:85]
	v_mfma_f32_16x16x32_bf16 v[66:69], v[156:159], v[214:217], v[66:69]
	v_mfma_f32_16x16x32_bf16 v[66:69], v[152:155], v[210:213], v[66:69]
	v_mfma_f32_16x16x32_bf16 v[126:129], v[160:163], v[180:183], v[126:129]
	v_mfma_f32_16x16x32_bf16 v[126:129], v[164:167], v[184:187], v[126:129]
	v_mfma_f32_16x16x32_bf16 v[110:113], v[164:167], v[192:195], v[110:113]
	v_mfma_f32_16x16x32_bf16 v[110:113], v[160:163], v[188:191], v[110:113]
	v_mfma_f32_16x16x32_bf16 v[94:97], v[160:163], v[202:205], v[94:97]
	v_mfma_f32_16x16x32_bf16 v[94:97], v[164:167], v[206:209], v[94:97]
	v_mfma_f32_16x16x32_bf16 v[78:81], v[164:167], v[214:217], v[78:81]
	v_mfma_f32_16x16x32_bf16 v[78:81], v[160:163], v[210:213], v[78:81]
	v_mfma_f32_16x16x32_bf16 v[122:125], v[168:171], v[180:183], v[122:125]
	v_mfma_f32_16x16x32_bf16 v[122:125], v[172:175], v[184:187], v[122:125]
	v_mfma_f32_16x16x32_bf16 v[106:109], v[172:175], v[192:195], v[106:109]
	v_mfma_f32_16x16x32_bf16 v[106:109], v[168:171], v[188:191], v[106:109]
	v_mfma_f32_16x16x32_bf16 v[90:93], v[168:171], v[202:205], v[90:93]
	v_mfma_f32_16x16x32_bf16 v[90:93], v[172:175], v[206:209], v[90:93]
	v_mfma_f32_16x16x32_bf16 v[74:77], v[172:175], v[214:217], v[74:77]
	v_mfma_f32_16x16x32_bf16 v[74:77], v[168:171], v[210:213], v[74:77]
	s_setprio 0
	s_barrier
; #define PG8_STAGE(bufoff, gbase, voff) do { _Pragma("unroll") for (int _i = 0; _i < 2; ++_i) \
;         __builtin_amdgcn_global_load_lds((const unsigned*)((const char*)(gbase) + (voff)[_i]), (PG8_LAS unsigned*)(lds + (bufoff) + ldsw + _i * 8192), 16, 0, 0); } while (0)
; #define PG8_LDA(dst, b, h) do { _Pragma("unroll") for (int m = 0; m < 4; ++m) _Pragma("unroll") for (int k = 0; k < 2; ++k) dst[m][k] = *(const PG8_LAS bf16x8*)(lds + PG8_SA(b, h) + aoff + m * 2048 + k * 1024); } while (0)
; #define PG8_WAIT_V(n) asm volatile("s_waitcnt vmcnt(" #n ")" ::: "memory")
; template <class Epi, class Sched, bool ALIGN_EPI = false, bool SP2 = false>
; __device__ __forceinline__ void gemm_phase(PG8_LAS unsigned char* lds, const Gemm g, const Sched& S, const Epi& E) {
;     ...
;             PG8_LDA(At, 1, 1); PG8_STAGE(PG8_SB(1, 0), b3, voffB); PG8_STAGE(PG8_SB(1, 1), b3 + hstep, voffB); PG8_STAGE(PG8_SA(1, 0), a3, voffA);
;             PG8_WAIT_V(8); PG8_WAIT_L(0); PG8_BAR; PG8_MMA(1, 0, At, B0); PG8_MMA(1, 1, At, B1); PG8_BAR; PG8_SCHED;
;             } else {
;             PG8_LDB(B0, 0, 0); PG8_SCHED; PG8_LDA(At, 0, 0); PG8_STAGE(PG8_SA(1, 1), a1 + hstep, voffA);
;             PG8_WAIT_L(8); PG8_BAR; PG8_WAIT_L(0); PG8_MMA(0, 0, At, B0); PG8_BAR; PG8_SCHED;
;             PG8_LDB(B1, 0, 1); PG8_STAGE(PG8_SB(0, 0), b2, voffB);
;             PG8_BAR; PG8_WAIT_L(0); PG8_MMA(0, 1, At, B1); PG8_BAR;
;             PG8_LDA(At, 0, 1); PG8_STAGE(PG8_SA(0, 0), a2, voffA);
;             PG8_BAR; PG8_WAIT_L(0); PG8_MMA(1, 0, At, B0); PG8_BAR; PG8_SCHED;
;             PG8_STAGE(PG8_SB(0, 1), b2 + hstep, voffB);
;             PG8_WAIT_V(6); PG8_BAR; PG8_MMA(1, 1, At, B1); PG8_BAR;
;             PG8_LDB(B0, 1, 0); PG8_SCHED; PG8_LDA(At, 1, 0); PG8_STAGE(PG8_SA(0, 1), a2 + hstep, voffA);
;             PG8_WAIT_L(8); PG8_BAR; PG8_WAIT_L(0); PG8_MMA(0, 0, At, B0); PG8_BAR; PG8_SCHED;
;             PG8_LDB(B1, 1, 1); PG8_STAGE(PG8_SB(1, 0), b3, voffB);
;             PG8_BAR; PG8_WAIT_L(0); PG8_MMA(0, 1, At, B1); PG8_BAR;
;             PG8_LDA(At, 1, 1); PG8_STAGE(PG8_SA(1, 0), a3, voffA);
;             PG8_BAR; PG8_WAIT_L(0); PG8_MMA(1, 0, At, B0); PG8_BAR; PG8_SCHED;
;             PG8_STAGE(PG8_SB(1, 1), b3 + hstep, voffB);
;             PG8_WAIT_V(6); PG8_BAR; PG8_MMA(1, 1, At, B1); PG8_BAR;
;             }
;         }
;         if constexpr (ALIGN_EPI) { if (wr == 0) PG8_BAR; }
	s_add_i32 s18, s18, s91
	v_lshl_add_u64 v[218:219], v[218:219], 0, s[30:31]
	s_mov_b32 m0, s18
	ds_read_b128 v[180:183], v178 offset:49152
	ds_read_b128 v[184:187], v178 offset:50176
	ds_read_b128 v[188:191], v178 offset:51200
	ds_read_b128 v[192:195], v178 offset:52224
	ds_read_b128 v[202:205], v178 offset:53248
	ds_read_b128 v[206:209], v178 offset:54272
	ds_read_b128 v[210:213], v178 offset:55296
	ds_read_b128 v[214:217], v178 offset:56320
	global_load_lds_dwordx4 v[218:219], off
	s_add_i32 m0, s18, 0x2000
	s_add_u32 s38, s44, 0x40080
	v_lshl_add_u64 v[218:219], v[220:221], 0, s[30:31]
	s_addc_u32 s39, s45, 0
	s_add_i32 s18, vcc_lo, s91
	global_load_lds_dwordx4 v[218:219], off
	v_lshl_add_u64 v[218:219], s[38:39], 0, v[134:135]
	s_mov_b32 m0, s18
	s_nop 0
	global_load_lds_dwordx4 v[218:219], off
	v_lshl_add_u64 v[218:219], s[38:39], 0, v[130:131]
	s_add_i32 m0, s18, 0x2000
	s_nop 0
	global_load_lds_dwordx4 v[218:219], off
	v_lshl_add_u64 v[218:219], v[222:223], 0, s[30:31]
	s_mov_b32 m0, s7
	s_nop 0
	global_load_lds_dwordx4 v[218:219], off
	v_lshl_add_u64 v[218:219], v[224:225], 0, s[30:31]
	s_mov_b32 m0, s96
	s_nop 0
	global_load_lds_dwordx4 v[218:219], off
	s_waitcnt vmcnt(8)
	s_waitcnt lgkmcnt(0)
	s_barrier
	s_setprio 1
	v_mfma_f32_16x16x32_bf16 v[54:57], v[144:147], v[180:183], v[54:57]
	v_mfma_f32_16x16x32_bf16 v[54:57], v[148:151], v[184:187], v[54:57]
	v_mfma_f32_16x16x32_bf16 v[38:41], v[148:151], v[192:195], v[38:41]
	v_mfma_f32_16x16x32_bf16 v[38:41], v[144:147], v[188:191], v[38:41]
	v_mfma_f32_16x16x32_bf16 v[22:25], v[144:147], v[202:205], v[22:25]
	v_mfma_f32_16x16x32_bf16 v[22:25], v[148:151], v[206:209], v[22:25]
	v_mfma_f32_16x16x32_bf16 v[6:9], v[148:151], v[214:217], v[6:9]
	v_mfma_f32_16x16x32_bf16 v[6:9], v[144:147], v[210:213], v[6:9]
	v_mfma_f32_16x16x32_bf16 v[50:53], v[152:155], v[180:183], v[50:53]
	v_mfma_f32_16x16x32_bf16 v[50:53], v[156:159], v[184:187], v[50:53]
	v_mfma_f32_16x16x32_bf16 v[34:37], v[156:159], v[192:195], v[34:37]
	v_mfma_f32_16x16x32_bf16 v[34:37], v[152:155], v[188:191], v[34:37]
	v_mfma_f32_16x16x32_bf16 v[18:21], v[152:155], v[202:205], v[18:21]
	v_mfma_f32_16x16x32_bf16 v[18:21], v[156:159], v[206:209], v[18:21]
	v_mfma_f32_16x16x32_bf16 v[2:5], v[156:159], v[214:217], v[2:5]
	v_mfma_f32_16x16x32_bf16 v[2:5], v[152:155], v[210:213], v[2:5]
	v_mfma_f32_16x16x32_bf16 v[62:65], v[160:163], v[180:183], v[62:65]
	v_mfma_f32_16x16x32_bf16 v[62:65], v[164:167], v[184:187], v[62:65]
	v_mfma_f32_16x16x32_bf16 v[46:49], v[164:167], v[192:195], v[46:49]
	v_mfma_f32_16x16x32_bf16 v[46:49], v[160:163], v[188:191], v[46:49]
	v_mfma_f32_16x16x32_bf16 v[30:33], v[160:163], v[202:205], v[30:33]
	v_mfma_f32_16x16x32_bf16 v[30:33], v[164:167], v[206:209], v[30:33]
	v_mfma_f32_16x16x32_bf16 v[10:13], v[164:167], v[214:217], v[10:13]
	v_mfma_f32_16x16x32_bf16 v[10:13], v[160:163], v[210:213], v[10:13]
	v_mfma_f32_16x16x32_bf16 v[58:61], v[168:171], v[180:183], v[58:61]
	v_mfma_f32_16x16x32_bf16 v[58:61], v[172:175], v[184:187], v[58:61]
	v_mfma_f32_16x16x32_bf16 v[42:45], v[172:175], v[192:195], v[42:45]
	v_mfma_f32_16x16x32_bf16 v[42:45], v[168:171], v[188:191], v[42:45]
	v_mfma_f32_16x16x32_bf16 v[26:29], v[168:171], v[202:205], v[26:29]
	v_mfma_f32_16x16x32_bf16 v[26:29], v[172:175], v[206:209], v[26:29]
	v_mfma_f32_16x16x32_bf16 v[14:17], v[172:175], v[214:217], v[14:17]
	v_mfma_f32_16x16x32_bf16 v[14:17], v[168:171], v[210:213], v[14:17]
	s_setprio 0
	s_barrier
	s_add_i32 s85, s85, 2
	s_add_u32 s46, s46, 0x100
	s_addc_u32 s47, s47, 0
	s_add_u32 s83, s83, 0x100
	s_addc_u32 s84, s84, 0
	s_cmp_gt_u32 s85, 13
	s_cbranch_scc0 .LBB0_132
	s_and_b64 vcc, exec, s[10:11]
	s_cbranch_vccz .LBB0_135
	s_barrier

; #define PG8_STAGE(bufoff, gbase, voff) do { _Pragma("unroll") for (int _i = 0; _i < 2; ++_i) \
;         __builtin_amdgcn_global_load_lds((const unsigned*)((const char*)(gbase) + (voff)[_i]), (PG8_LAS unsigned*)(lds + (bufoff) + ldsw + _i * 8192), 16, 0, 0); } while (0)
; #define PG8_LDA(dst, b, h) do { _Pragma("unroll") for (int m = 0; m < 4; ++m) _Pragma("unroll") for (int k = 0; k < 2; ++k) dst[m][k] = *(const PG8_LAS bf16x8*)(lds + PG8_SA(b, h) + aoff + m * 2048 + k * 1024); } while (0)
; #define PG8_LDB(dst, b, h) do { _Pragma("unroll") for (int n = 0; n < 2; ++n) _Pragma("unroll") for (int k = 0; k < 2; ++k) dst[n][k] = *(const PG8_LAS bf16x8*)(lds + PG8_SB(b, h) + boff + n * 2048 + k * 1024); } while (0)
; #define PG8_MMA(ai, bj, At, Bt) do { __builtin_amdgcn_s_setprio(1); _Pragma("unroll") for (int m = 0; m < 4; ++m) _Pragma("unroll") for (int n = 0; n < 2; ++n) _Pragma("unroll") for (int k = 0; k < 2; ++k) \
;         acc[ai][bj][m][n] = __builtin_amdgcn_mfma_f32_16x16x32_bf16(Bt[n][k], At[m][k], acc[ai][bj][m][n], 0, 0, 0); __builtin_amdgcn_s_setprio(0); } while (0)
; #define PG8_WAIT_V(n) asm volatile("s_waitcnt vmcnt(" #n ")" ::: "memory")
; #define PG8_WAIT_L(n) asm volatile("s_waitcnt lgkmcnt(" #n ")" ::: "memory")
; template <class Epi, class Sched, bool ALIGN_EPI = false, bool SP2 = false>
; __device__ __forceinline__ void gemm_phase(PG8_LAS unsigned char* lds, const Gemm g, const Sched& S, const Epi& E) {
;     ...
;             const bool last = (t == nt - 2);
;             const char* a1 = cA + (size_t)(t + 1) * kstep;
;             const char* a2 = last ? nA : cA + (size_t)(t + 2) * kstep; const char* b2 = last ? nB : cB + (size_t)(t + 2) * kstep;
;             const char* a3 = a2 + kstep; const char* b3 = b2 + kstep;
;             if (last && has_next) S.a_ready(nxt);
;             if constexpr (SP2) {
;             PG8_LDB(B0, 0, 0); PG8_LDB(B1, 0, 1); PG8_SCHED; PG8_LDA(At, 0, 0); PG8_STAGE(PG8_SA(1, 1), a1 + hstep, voffA);
;             PG8_WAIT_V(8); PG8_WAIT_L(0); PG8_BAR; PG8_MMA(0, 0, At, B0); PG8_MMA(0, 1, At, B1); PG8_BAR; PG8_SCHED;
;             PG8_LDA(At, 0, 1); PG8_STAGE(PG8_SB(0, 0), b2, voffB); PG8_STAGE(PG8_SB(0, 1), b2 + hstep, voffB); PG8_STAGE(PG8_SA(0, 0), a2, voffA);
;             PG8_WAIT_V(8); PG8_WAIT_L(0); PG8_BAR; PG8_MMA(1, 0, At, B0); PG8_MMA(1, 1, At, B1); PG8_BAR; PG8_SCHED;
.LBB0_220:
	s_add_u32 s18, s60, 0xfffc0080
	s_addc_u32 s38, s61, -1
	s_add_i32 s39, 0, 0x10000
	s_cmp_eq_u32 s82, 12
	s_cselect_b32 s65, s47, s38
	s_cselect_b32 s64, s78, s18
	v_add_u32_e32 v145, s39, v141
	s_cselect_b32 s57, s49, s81
	s_cselect_b32 s56, s79, s80
	s_add_i32 s18, 0, 0x14000
	ds_read_b128 v[146:149], v145
	ds_read_b128 v[150:153], v145 offset:1024
	ds_read_b128 v[154:157], v145 offset:2048
	ds_read_b128 v[158:161], v145 offset:3072
	v_add_u32_e32 v145, s18, v141
	ds_read_b128 v[162:165], v145
	ds_read_b128 v[166:169], v145 offset:1024
	ds_read_b128 v[170:173], v145 offset:2048
	ds_read_b128 v[174:177], v145 offset:3072
	v_lshl_add_u64 v[194:195], s[60:61], 0, v[136:137]
	s_add_i32 m0, s29, 0xc000
	ds_read_b128 v[178:181], v144
	ds_read_b128 v[182:185], v144 offset:1024
	ds_read_b128 v[186:189], v144 offset:2048
	ds_read_b128 v[190:193], v144 offset:3072
	ds_read_b128 v[202:205], v144 offset:4096
	ds_read_b128 v[206:209], v144 offset:5120
	ds_read_b128 v[210:213], v144 offset:6144
	ds_read_b128 v[214:217], v144 offset:7168
	global_load_lds_dwordx4 v[194:195], off
	v_lshl_add_u64 v[194:195], s[60:61], 0, v[138:139]
	s_add_i32 m0, s29, 0xe000
	s_nop 0
	global_load_lds_dwordx4 v[194:195], off
	s_waitcnt vmcnt(8)
	s_waitcnt lgkmcnt(0)
	s_barrier
	s_setprio 1
	v_mfma_f32_16x16x32_bf16 v[114:117], v[146:149], v[178:181], v[114:117]
	v_mfma_f32_16x16x32_bf16 v[114:117], v[150:153], v[182:185], v[114:117]
	v_mfma_f32_16x16x32_bf16 v[98:101], v[150:153], v[190:193], v[98:101]
	v_mfma_f32_16x16x32_bf16 v[98:101], v[146:149], v[186:189], v[98:101]
	v_mfma_f32_16x16x32_bf16 v[82:85], v[146:149], v[202:205], v[82:85]
	v_mfma_f32_16x16x32_bf16 v[82:85], v[150:153], v[206:209], v[82:85]
	v_mfma_f32_16x16x32_bf16 v[66:69], v[150:153], v[214:217], v[66:69]
	v_mfma_f32_16x16x32_bf16 v[66:69], v[146:149], v[210:213], v[66:69]
	v_mfma_f32_16x16x32_bf16 v[118:121], v[154:157], v[178:181], v[118:121]
	v_mfma_f32_16x16x32_bf16 v[118:121], v[158:161], v[182:185], v[118:121]
	v_mfma_f32_16x16x32_bf16 v[102:105], v[158:161], v[190:193], v[102:105]
	v_mfma_f32_16x16x32_bf16 v[102:105], v[154:157], v[186:189], v[102:105]
	v_mfma_f32_16x16x32_bf16 v[86:89], v[154:157], v[202:205], v[86:89]
	v_mfma_f32_16x16x32_bf16 v[86:89], v[158:161], v[206:209], v[86:89]
	v_mfma_f32_16x16x32_bf16 v[70:73], v[158:161], v[214:217], v[70:73]
	v_mfma_f32_16x16x32_bf16 v[70:73], v[154:157], v[210:213], v[70:73]
	v_mfma_f32_16x16x32_bf16 v[122:125], v[162:165], v[178:181], v[122:125]
	v_mfma_f32_16x16x32_bf16 v[122:125], v[166:169], v[182:185], v[122:125]
	v_mfma_f32_16x16x32_bf16 v[106:109], v[166:169], v[190:193], v[106:109]
	v_mfma_f32_16x16x32_bf16 v[106:109], v[162:165], v[186:189], v[106:109]
	v_mfma_f32_16x16x32_bf16 v[90:93], v[162:165], v[202:205], v[90:93]
	v_mfma_f32_16x16x32_bf16 v[90:93], v[166:169], v[206:209], v[90:93]
	v_mfma_f32_16x16x32_bf16 v[74:77], v[166:169], v[214:217], v[74:77]
	v_mfma_f32_16x16x32_bf16 v[74:77], v[162:165], v[210:213], v[74:77]
	v_mfma_f32_16x16x32_bf16 v[126:129], v[170:173], v[178:181], v[126:129]
	v_mfma_f32_16x16x32_bf16 v[126:129], v[174:177], v[182:185], v[126:129]
	v_mfma_f32_16x16x32_bf16 v[110:113], v[174:177], v[190:193], v[110:113]
	v_mfma_f32_16x16x32_bf16 v[110:113], v[170:173], v[186:189], v[110:113]
	v_mfma_f32_16x16x32_bf16 v[94:97], v[170:173], v[202:205], v[94:97]
	v_mfma_f32_16x16x32_bf16 v[94:97], v[174:177], v[206:209], v[94:97]
	v_mfma_f32_16x16x32_bf16 v[78:81], v[174:177], v[214:217], v[78:81]
	v_mfma_f32_16x16x32_bf16 v[78:81], v[170:173], v[210:213], v[78:81]
	s_setprio 0
	s_barrier
	s_add_i32 s38, s39, s27
	v_lshl_add_u64 v[194:195], s[56:57], 0, v[0:1]
	s_mov_b32 m0, s38
	ds_read_b128 v[178:181], v144 offset:16384
	ds_read_b128 v[182:185], v144 offset:17408
	ds_read_b128 v[186:189], v144 offset:18432
	ds_read_b128 v[190:193], v144 offset:19456
	ds_read_b128 v[202:205], v144 offset:20480
	ds_read_b128 v[206:209], v144 offset:21504
	ds_read_b128 v[210:213], v144 offset:22528
	ds_read_b128 v[214:217], v144 offset:23552
	global_load_lds_dwordx4 v[194:195], off
	s_add_i32 m0, s38, 0x2000
	s_add_u32 s38, s56, 0x40000
	v_lshl_add_u64 v[218:219], s[56:57], 0, v[130:131]
	s_addc_u32 s39, s57, 0
	s_add_i32 s18, s18, s27
	global_load_lds_dwordx4 v[218:219], off
	v_lshl_add_u64 v[220:221], s[38:39], 0, v[0:1]
	s_mov_b32 m0, s18
	v_lshl_add_u64 v[222:223], s[64:65], 0, v[132:133]
	global_load_lds_dwordx4 v[220:221], off
	v_lshl_add_u64 v[220:221], s[38:39], 0, v[130:131]
	s_add_i32 m0, s18, 0x2000
	s_nop 0
	global_load_lds_dwordx4 v[220:221], off
	v_lshl_add_u64 v[220:221], s[64:65], 0, v[134:135]
	s_mov_b32 m0, s29
	s_nop 0
	global_load_lds_dwordx4 v[220:221], off
	s_mov_b32 m0, s33
	s_nop 0
	global_load_lds_dwordx4 v[222:223], off
	s_waitcnt vmcnt(8)
	s_waitcnt lgkmcnt(0)
	s_barrier
; #define PG8_STAGE(bufoff, gbase, voff) do { _Pragma("unroll") for (int _i = 0; _i < 2; ++_i) \
;         __builtin_amdgcn_global_load_lds((const unsigned*)((const char*)(gbase) + (voff)[_i]), (PG8_LAS unsigned*)(lds + (bufoff) + ldsw + _i * 8192), 16, 0, 0); } while (0)
; #define PG8_LDA(dst, b, h) do { _Pragma("unroll") for (int m = 0; m < 4; ++m) _Pragma("unroll") for (int k = 0; k < 2; ++k) dst[m][k] = *(const PG8_LAS bf16x8*)(lds + PG8_SA(b, h) + aoff + m * 2048 + k * 1024); } while (0)
; #define PG8_LDB(dst, b, h) do { _Pragma("unroll") for (int n = 0; n < 2; ++n) _Pragma("unroll") for (int k = 0; k < 2; ++k) dst[n][k] = *(const PG8_LAS bf16x8*)(lds + PG8_SB(b, h) + boff + n * 2048 + k * 1024); } while (0)
; #define PG8_MMA(ai, bj, At, Bt) do { __builtin_amdgcn_s_setprio(1); _Pragma("unroll") for (int m = 0; m < 4; ++m) _Pragma("unroll") for (int n = 0; n < 2; ++n) _Pragma("unroll") for (int k = 0; k < 2; ++k) \
;         acc[ai][bj][m][n] = __builtin_amdgcn_mfma_f32_16x16x32_bf16(Bt[n][k], At[m][k], acc[ai][bj][m][n], 0, 0, 0); __builtin_amdgcn_s_setprio(0); } while (0)
; #define PG8_WAIT_V(n) asm volatile("s_waitcnt vmcnt(" #n ")" ::: "memory")
; #define PG8_WAIT_L(n) asm volatile("s_waitcnt lgkmcnt(" #n ")" ::: "memory")
; #define PG8_BAR __builtin_amdgcn_s_barrier()
; #define PG8_SCHED __builtin_amdgcn_sched_barrier(0)
; template <class Epi, class Sched, bool ALIGN_EPI = false, bool SP2 = false>
; __device__ __forceinline__ void gemm_phase(PG8_LAS unsigned char* lds, const Gemm g, const Sched& S, const Epi& E) {
;     ...
;             PG8_WAIT_V(8); PG8_WAIT_L(0); PG8_BAR; PG8_MMA(1, 0, At, B0); PG8_MMA(1, 1, At, B1); PG8_BAR; PG8_SCHED;
;             PG8_LDB(B0, 1, 0); PG8_LDB(B1, 1, 1); PG8_SCHED; PG8_LDA(At, 1, 0); PG8_STAGE(PG8_SA(0, 1), a2 + hstep, voffA);
;             PG8_WAIT_V(8); PG8_WAIT_L(0); PG8_BAR; PG8_MMA(0, 0, At, B0); PG8_MMA(0, 1, At, B1); PG8_BAR; PG8_SCHED;
	s_setprio 1
	v_mfma_f32_16x16x32_bf16 v[50:53], v[146:149], v[178:181], v[50:53]
	v_mfma_f32_16x16x32_bf16 v[50:53], v[150:153], v[182:185], v[50:53]
	v_mfma_f32_16x16x32_bf16 v[34:37], v[150:153], v[190:193], v[34:37]
	v_mfma_f32_16x16x32_bf16 v[34:37], v[146:149], v[186:189], v[34:37]
	v_mfma_f32_16x16x32_bf16 v[18:21], v[146:149], v[202:205], v[18:21]
	v_mfma_f32_16x16x32_bf16 v[18:21], v[150:153], v[206:209], v[18:21]
	v_mfma_f32_16x16x32_bf16 v[2:5], v[150:153], v[214:217], v[2:5]
	v_mfma_f32_16x16x32_bf16 v[2:5], v[146:149], v[210:213], v[2:5]
	v_mfma_f32_16x16x32_bf16 v[54:57], v[154:157], v[178:181], v[54:57]
	v_mfma_f32_16x16x32_bf16 v[54:57], v[158:161], v[182:185], v[54:57]
	v_mfma_f32_16x16x32_bf16 v[38:41], v[158:161], v[190:193], v[38:41]
	v_mfma_f32_16x16x32_bf16 v[38:41], v[154:157], v[186:189], v[38:41]
	v_mfma_f32_16x16x32_bf16 v[22:25], v[154:157], v[202:205], v[22:25]
	v_mfma_f32_16x16x32_bf16 v[22:25], v[158:161], v[206:209], v[22:25]
	v_mfma_f32_16x16x32_bf16 v[6:9], v[158:161], v[214:217], v[6:9]
	v_mfma_f32_16x16x32_bf16 v[6:9], v[154:157], v[210:213], v[6:9]
	v_mfma_f32_16x16x32_bf16 v[58:61], v[162:165], v[178:181], v[58:61]
	v_mfma_f32_16x16x32_bf16 v[58:61], v[166:169], v[182:185], v[58:61]
	v_mfma_f32_16x16x32_bf16 v[42:45], v[166:169], v[190:193], v[42:45]
	v_mfma_f32_16x16x32_bf16 v[42:45], v[162:165], v[186:189], v[42:45]
	v_mfma_f32_16x16x32_bf16 v[26:29], v[162:165], v[202:205], v[26:29]
	v_mfma_f32_16x16x32_bf16 v[26:29], v[166:169], v[206:209], v[26:29]
	v_mfma_f32_16x16x32_bf16 v[10:13], v[166:169], v[214:217], v[10:13]
	v_mfma_f32_16x16x32_bf16 v[10:13], v[162:165], v[210:213], v[10:13]
	v_mfma_f32_16x16x32_bf16 v[62:65], v[170:173], v[178:181], v[62:65]
	v_mfma_f32_16x16x32_bf16 v[62:65], v[174:177], v[182:185], v[62:65]
	v_mfma_f32_16x16x32_bf16 v[46:49], v[174:177], v[190:193], v[46:49]
	v_mfma_f32_16x16x32_bf16 v[46:49], v[170:173], v[186:189], v[46:49]
	v_mfma_f32_16x16x32_bf16 v[30:33], v[170:173], v[202:205], v[30:33]
	v_mfma_f32_16x16x32_bf16 v[30:33], v[174:177], v[206:209], v[30:33]
	v_mfma_f32_16x16x32_bf16 v[14:17], v[174:177], v[214:217], v[14:17]
	v_mfma_f32_16x16x32_bf16 v[14:17], v[170:173], v[210:213], v[14:17]
	s_setprio 0
	s_barrier
	s_add_i32 s18, 0, 0x18000
	v_add_u32_e32 v145, s18, v141
	s_add_i32 s83, 0, 0x1c000
	ds_read_b128 v[146:149], v145
	ds_read_b128 v[150:153], v145 offset:1024
	ds_read_b128 v[154:157], v145 offset:2048
	ds_read_b128 v[158:161], v145 offset:3072
	v_add_u32_e32 v145, s83, v141
	ds_read_b128 v[162:165], v145
	ds_read_b128 v[166:169], v145 offset:1024
	ds_read_b128 v[170:173], v145 offset:2048
	ds_read_b128 v[174:177], v145 offset:3072
	s_add_u32 s38, s64, 0x40000
	s_addc_u32 s39, s65, 0
	s_mov_b32 m0, s58
	v_lshl_add_u64 v[224:225], s[38:39], 0, v[134:135]
	ds_read_b128 v[178:181], v144 offset:32768
	ds_read_b128 v[182:185], v144 offset:33792
	ds_read_b128 v[186:189], v144 offset:34816
	ds_read_b128 v[190:193], v144 offset:35840
	ds_read_b128 v[202:205], v144 offset:36864
	ds_read_b128 v[206:209], v144 offset:37888
	ds_read_b128 v[210:213], v144 offset:38912
	ds_read_b128 v[214:217], v144 offset:39936
	global_load_lds_dwordx4 v[224:225], off
	v_lshl_add_u64 v[224:225], s[38:39], 0, v[132:133]
	s_mov_b32 m0, s69
	s_nop 0
	global_load_lds_dwordx4 v[224:225], off
	s_waitcnt vmcnt(8)
	s_waitcnt lgkmcnt(0)
	s_barrier
	s_setprio 1
	v_mfma_f32_16x16x32_bf16 v[114:117], v[146:149], v[178:181], v[114:117]
	v_mfma_f32_16x16x32_bf16 v[114:117], v[150:153], v[182:185], v[114:117]
	v_mfma_f32_16x16x32_bf16 v[98:101], v[150:153], v[190:193], v[98:101]
	v_mfma_f32_16x16x32_bf16 v[98:101], v[146:149], v[186:189], v[98:101]
	v_mfma_f32_16x16x32_bf16 v[82:85], v[146:149], v[202:205], v[82:85]
	v_mfma_f32_16x16x32_bf16 v[82:85], v[150:153], v[206:209], v[82:85]
	v_mfma_f32_16x16x32_bf16 v[66:69], v[150:153], v[214:217], v[66:69]
	v_mfma_f32_16x16x32_bf16 v[66:69], v[146:149], v[210:213], v[66:69]
	v_mfma_f32_16x16x32_bf16 v[118:121], v[154:157], v[178:181], v[118:121]
	v_mfma_f32_16x16x32_bf16 v[118:121], v[158:161], v[182:185], v[118:121]
	v_mfma_f32_16x16x32_bf16 v[102:105], v[158:161], v[190:193], v[102:105]
	v_mfma_f32_16x16x32_bf16 v[102:105], v[154:157], v[186:189], v[102:105]
	v_mfma_f32_16x16x32_bf16 v[86:89], v[154:157], v[202:205], v[86:89]
	v_mfma_f32_16x16x32_bf16 v[86:89], v[158:161], v[206:209], v[86:89]
	v_mfma_f32_16x16x32_bf16 v[70:73], v[158:161], v[214:217], v[70:73]
	v_mfma_f32_16x16x32_bf16 v[70:73], v[154:157], v[210:213], v[70:73]
	v_mfma_f32_16x16x32_bf16 v[122:125], v[162:165], v[178:181], v[122:125]
	v_mfma_f32_16x16x32_bf16 v[122:125], v[166:169], v[182:185], v[122:125]
	v_mfma_f32_16x16x32_bf16 v[106:109], v[166:169], v[190:193], v[106:109]
	v_mfma_f32_16x16x32_bf16 v[106:109], v[162:165], v[186:189], v[106:109]
	v_mfma_f32_16x16x32_bf16 v[90:93], v[162:165], v[202:205], v[90:93]
	v_mfma_f32_16x16x32_bf16 v[90:93], v[166:169], v[206:209], v[90:93]
	v_mfma_f32_16x16x32_bf16 v[74:77], v[166:169], v[214:217], v[74:77]
	v_mfma_f32_16x16x32_bf16 v[74:77], v[162:165], v[210:213], v[74:77]
	v_mfma_f32_16x16x32_bf16 v[126:129], v[170:173], v[178:181], v[126:129]
	v_mfma_f32_16x16x32_bf16 v[126:129], v[174:177], v[182:185], v[126:129]
	v_mfma_f32_16x16x32_bf16 v[110:113], v[174:177], v[190:193], v[110:113]
	v_mfma_f32_16x16x32_bf16 v[110:113], v[170:173], v[186:189], v[110:113]
	v_mfma_f32_16x16x32_bf16 v[94:97], v[170:173], v[202:205], v[94:97]
	v_mfma_f32_16x16x32_bf16 v[94:97], v[174:177], v[206:209], v[94:97]
	v_mfma_f32_16x16x32_bf16 v[78:81], v[174:177], v[214:217], v[78:81]
	v_mfma_f32_16x16x32_bf16 v[78:81], v[170:173], v[210:213], v[78:81]
	s_setprio 0
	s_barrier
; #define PG8_STAGE(bufoff, gbase, voff) do { _Pragma("unroll") for (int _i = 0; _i < 2; ++_i) \
;         __builtin_amdgcn_global_load_lds((const unsigned*)((const char*)(gbase) + (voff)[_i]), (PG8_LAS unsigned*)(lds + (bufoff) + ldsw + _i * 8192), 16, 0, 0); } while (0)
; #define PG8_LDA(dst, b, h) do { _Pragma("unroll") for (int m = 0; m < 4; ++m) _Pragma("unroll") for (int k = 0; k < 2; ++k) dst[m][k] = *(const PG8_LAS bf16x8*)(lds + PG8_SA(b, h) + aoff + m * 2048 + k * 1024); } while (0)
; #define PG8_WAIT_V(n) asm volatile("s_waitcnt vmcnt(" #n ")" ::: "memory")
; template <class Epi, class Sched, bool ALIGN_EPI = false, bool SP2 = false>
; __device__ __forceinline__ void gemm_phase(PG8_LAS unsigned char* lds, const Gemm g, const Sched& S, const Epi& E) {
;     ...
;             PG8_LDA(At, 1, 1); PG8_STAGE(PG8_SB(1, 0), b3, voffB); PG8_STAGE(PG8_SB(1, 1), b3 + hstep, voffB); PG8_STAGE(PG8_SA(1, 0), a3, voffA);
;             PG8_WAIT_V(8); PG8_WAIT_L(0); PG8_BAR; PG8_MMA(1, 0, At, B0); PG8_MMA(1, 1, At, B1); PG8_BAR; PG8_SCHED;
;             } else {
;             PG8_LDB(B0, 0, 0); PG8_SCHED; PG8_LDA(At, 0, 0); PG8_STAGE(PG8_SA(1, 1), a1 + hstep, voffA);
;             PG8_WAIT_L(8); PG8_BAR; PG8_WAIT_L(0); PG8_MMA(0, 0, At, B0); PG8_BAR; PG8_SCHED;
;             PG8_LDB(B1, 0, 1); PG8_STAGE(PG8_SB(0, 0), b2, voffB);
;             PG8_BAR; PG8_WAIT_L(0); PG8_MMA(0, 1, At, B1); PG8_BAR;
;             PG8_LDA(At, 0, 1); PG8_STAGE(PG8_SA(0, 0), a2, voffA);
;             PG8_BAR; PG8_WAIT_L(0); PG8_MMA(1, 0, At, B0); PG8_BAR; PG8_SCHED;
;             PG8_STAGE(PG8_SB(0, 1), b2 + hstep, voffB);
;             PG8_WAIT_V(6); PG8_BAR; PG8_MMA(1, 1, At, B1); PG8_BAR;
;             PG8_LDB(B0, 1, 0); PG8_SCHED; PG8_LDA(At, 1, 0); PG8_STAGE(PG8_SA(0, 1), a2 + hstep, voffA);
;             PG8_WAIT_L(8); PG8_BAR; PG8_WAIT_L(0); PG8_MMA(0, 0, At, B0); PG8_BAR; PG8_SCHED;
;             PG8_LDB(B1, 1, 1); PG8_STAGE(PG8_SB(1, 0), b3, voffB);
;             PG8_BAR; PG8_WAIT_L(0); PG8_MMA(0, 1, At, B1); PG8_BAR;
;             PG8_LDA(At, 1, 1); PG8_STAGE(PG8_SA(1, 0), a3, voffA);
;             PG8_BAR; PG8_WAIT_L(0); PG8_MMA(1, 0, At, B0); PG8_BAR; PG8_SCHED;
;             PG8_STAGE(PG8_SB(1, 1), b3 + hstep, voffB);
;             PG8_WAIT_V(6); PG8_BAR; PG8_MMA(1, 1, At, B1); PG8_BAR;
;             }
;         }
;         if constexpr (ALIGN_EPI) { if (wr == 0) PG8_BAR; }
	s_add_i32 s18, s18, s27
	v_lshl_add_u64 v[194:195], v[194:195], 0, s[30:31]
	s_mov_b32 m0, s18
	ds_read_b128 v[178:181], v144 offset:49152
	ds_read_b128 v[182:185], v144 offset:50176
	ds_read_b128 v[186:189], v144 offset:51200
	ds_read_b128 v[190:193], v144 offset:52224
	ds_read_b128 v[202:205], v144 offset:53248
	ds_read_b128 v[206:209], v144 offset:54272
	ds_read_b128 v[210:213], v144 offset:55296
	ds_read_b128 v[214:217], v144 offset:56320
	global_load_lds_dwordx4 v[194:195], off
	s_add_i32 m0, s18, 0x2000
	s_add_u32 s38, s56, 0x40080
	v_lshl_add_u64 v[194:195], v[218:219], 0, s[30:31]
	s_addc_u32 s39, s57, 0
	s_add_i32 s18, s83, s27
	global_load_lds_dwordx4 v[194:195], off
	v_lshl_add_u64 v[194:195], s[38:39], 0, v[0:1]
	s_mov_b32 m0, s18
	s_nop 0
	global_load_lds_dwordx4 v[194:195], off
	v_lshl_add_u64 v[194:195], s[38:39], 0, v[130:131]
	s_add_i32 m0, s18, 0x2000
	s_nop 0
	global_load_lds_dwordx4 v[194:195], off
	v_lshl_add_u64 v[194:195], v[220:221], 0, s[30:31]
	s_mov_b32 m0, s71
	s_nop 0
	global_load_lds_dwordx4 v[194:195], off
	v_lshl_add_u64 v[194:195], v[222:223], 0, s[30:31]
	s_mov_b32 m0, s72
	s_nop 0
	global_load_lds_dwordx4 v[194:195], off
	s_waitcnt vmcnt(8)
	s_waitcnt lgkmcnt(0)
	s_barrier
	s_setprio 1
	v_mfma_f32_16x16x32_bf16 v[50:53], v[146:149], v[178:181], v[50:53]
	v_mfma_f32_16x16x32_bf16 v[50:53], v[150:153], v[182:185], v[50:53]
	v_mfma_f32_16x16x32_bf16 v[34:37], v[150:153], v[190:193], v[34:37]
	v_mfma_f32_16x16x32_bf16 v[34:37], v[146:149], v[186:189], v[34:37]
	v_mfma_f32_16x16x32_bf16 v[18:21], v[146:149], v[202:205], v[18:21]
	v_mfma_f32_16x16x32_bf16 v[18:21], v[150:153], v[206:209], v[18:21]
	v_mfma_f32_16x16x32_bf16 v[2:5], v[150:153], v[214:217], v[2:5]
	v_mfma_f32_16x16x32_bf16 v[2:5], v[146:149], v[210:213], v[2:5]
	v_mfma_f32_16x16x32_bf16 v[54:57], v[154:157], v[178:181], v[54:57]
	v_mfma_f32_16x16x32_bf16 v[54:57], v[158:161], v[182:185], v[54:57]
	v_mfma_f32_16x16x32_bf16 v[38:41], v[158:161], v[190:193], v[38:41]
	v_mfma_f32_16x16x32_bf16 v[38:41], v[154:157], v[186:189], v[38:41]
	v_mfma_f32_16x16x32_bf16 v[22:25], v[154:157], v[202:205], v[22:25]
	v_mfma_f32_16x16x32_bf16 v[22:25], v[158:161], v[206:209], v[22:25]
	v_mfma_f32_16x16x32_bf16 v[6:9], v[158:161], v[214:217], v[6:9]
	v_mfma_f32_16x16x32_bf16 v[6:9], v[154:157], v[210:213], v[6:9]
	v_mfma_f32_16x16x32_bf16 v[58:61], v[162:165], v[178:181], v[58:61]
	v_mfma_f32_16x16x32_bf16 v[58:61], v[166:169], v[182:185], v[58:61]
	v_mfma_f32_16x16x32_bf16 v[42:45], v[166:169], v[190:193], v[42:45]
	v_mfma_f32_16x16x32_bf16 v[42:45], v[162:165], v[186:189], v[42:45]
	v_mfma_f32_16x16x32_bf16 v[26:29], v[162:165], v[202:205], v[26:29]
	v_mfma_f32_16x16x32_bf16 v[26:29], v[166:169], v[206:209], v[26:29]
	v_mfma_f32_16x16x32_bf16 v[10:13], v[166:169], v[214:217], v[10:13]
	v_mfma_f32_16x16x32_bf16 v[10:13], v[162:165], v[210:213], v[10:13]
	v_mfma_f32_16x16x32_bf16 v[62:65], v[170:173], v[178:181], v[62:65]
	v_mfma_f32_16x16x32_bf16 v[62:65], v[174:177], v[182:185], v[62:65]
	v_mfma_f32_16x16x32_bf16 v[46:49], v[174:177], v[190:193], v[46:49]
	v_mfma_f32_16x16x32_bf16 v[46:49], v[170:173], v[186:189], v[46:49]
	v_mfma_f32_16x16x32_bf16 v[30:33], v[170:173], v[202:205], v[30:33]
	v_mfma_f32_16x16x32_bf16 v[30:33], v[174:177], v[206:209], v[30:33]
	v_mfma_f32_16x16x32_bf16 v[14:17], v[174:177], v[214:217], v[14:17]
	v_mfma_f32_16x16x32_bf16 v[14:17], v[170:173], v[210:213], v[14:17]
	s_setprio 0
	s_barrier
	s_add_i32 s82, s82, 2
	s_add_u32 s60, s60, 0x100
	s_addc_u32 s61, s61, 0
	s_add_u32 s80, s80, 0x100
	s_addc_u32 s81, s81, 0
	s_cmp_gt_u32 s82, 13
	s_cbranch_scc0 .LBB0_220
	s_and_b64 vcc, exec, s[44:45]
	s_cbranch_vccz .LBB0_223
	s_barrier

; #define PG8_STAGE(bufoff, gbase, voff) do { _Pragma("unroll") for (int _i = 0; _i < 2; ++_i) \
;         __builtin_amdgcn_global_load_lds((const unsigned*)((const char*)(gbase) + (voff)[_i]), (PG8_LAS unsigned*)(lds + (bufoff) + ldsw + _i * 8192), 16, 0, 0); } while (0)
; #define PG8_LDA(dst, b, h) do { _Pragma("unroll") for (int m = 0; m < 4; ++m) _Pragma("unroll") for (int k = 0; k < 2; ++k) dst[m][k] = *(const PG8_LAS bf16x8*)(lds + PG8_SA(b, h) + aoff + m * 2048 + k * 1024); } while (0)
; #define PG8_LDB(dst, b, h) do { _Pragma("unroll") for (int n = 0; n < 2; ++n) _Pragma("unroll") for (int k = 0; k < 2; ++k) dst[n][k] = *(const PG8_LAS bf16x8*)(lds + PG8_SB(b, h) + boff + n * 2048 + k * 1024); } while (0)
; #define PG8_MMA(ai, bj, At, Bt) do { __builtin_amdgcn_s_setprio(1); _Pragma("unroll") for (int m = 0; m < 4; ++m) _Pragma("unroll") for (int n = 0; n < 2; ++n) _Pragma("unroll") for (int k = 0; k < 2; ++k) \
;         acc[ai][bj][m][n] = __builtin_amdgcn_mfma_f32_16x16x32_bf16(Bt[n][k], At[m][k], acc[ai][bj][m][n], 0, 0, 0); __builtin_amdgcn_s_setprio(0); } while (0)
; #define PG8_WAIT_V(n) asm volatile("s_waitcnt vmcnt(" #n ")" ::: "memory")
; #define PG8_WAIT_L(n) asm volatile("s_waitcnt lgkmcnt(" #n ")" ::: "memory")
; template <class Epi, class Sched, bool ALIGN_EPI = false, bool SP2 = false>
; __device__ __forceinline__ void gemm_phase(PG8_LAS unsigned char* lds, const Gemm g, const Sched& S, const Epi& E) {
;     ...
;             const bool last = (t == nt - 2);
;             const char* a1 = cA + (size_t)(t + 1) * kstep;
;             const char* a2 = last ? nA : cA + (size_t)(t + 2) * kstep; const char* b2 = last ? nB : cB + (size_t)(t + 2) * kstep;
;             const char* a3 = a2 + kstep; const char* b3 = b2 + kstep;
;             if (last && has_next) S.a_ready(nxt);
;             if constexpr (SP2) {
;             PG8_LDB(B0, 0, 0); PG8_LDB(B1, 0, 1); PG8_SCHED; PG8_LDA(At, 0, 0); PG8_STAGE(PG8_SA(1, 1), a1 + hstep, voffA);
;             PG8_WAIT_V(8); PG8_WAIT_L(0); PG8_BAR; PG8_MMA(0, 0, At, B0); PG8_MMA(0, 1, At, B1); PG8_BAR; PG8_SCHED;
;             PG8_LDA(At, 0, 1); PG8_STAGE(PG8_SB(0, 0), b2, voffB); PG8_STAGE(PG8_SB(0, 1), b2 + hstep, voffB); PG8_STAGE(PG8_SA(0, 0), a2, voffA);
;             PG8_WAIT_V(8); PG8_WAIT_L(0); PG8_BAR; PG8_MMA(1, 0, At, B0); PG8_MMA(1, 1, At, B1); PG8_BAR; PG8_SCHED;
.LBB0_274:
	s_add_i32 vcc_lo, s46, 2
	s_add_u32 s38, s48, 0x80
	s_addc_u32 s39, s49, 0
	s_add_i32 vcc_hi, 0, 0x10000
	s_cmp_eq_u32 s99, s46
	s_cselect_b32 s47, s81, s39
	s_cselect_b32 s46, s80, s38
	s_cselect_b32 s39, s83, s51
	s_cselect_b32 s38, s82, s50
	s_add_i32 s18, 0, 0x14000
	v_add_u32_e32 v142, vcc_hi, v245
	v_add_u32_e32 v158, s18, v245
	ds_read_b128 v[110:113], v142
	ds_read_b128 v[118:121], v142 offset:1024
	ds_read_b128 v[138:141], v142 offset:2048
	ds_read_b128 v[142:145], v142 offset:3072
	ds_read_b128 v[146:149], v158
	ds_read_b128 v[150:153], v158 offset:1024
	ds_read_b128 v[154:157], v158 offset:2048
	ds_read_b128 v[158:161], v158 offset:3072
	v_lshl_add_u64 v[210:211], s[48:49], 0, v[206:207]
	s_add_i32 m0, s92, 0xc000
	ds_read_b128 v[162:165], v247
	ds_read_b128 v[166:169], v247 offset:1024
	ds_read_b128 v[170:173], v247 offset:2048
	ds_read_b128 v[174:177], v247 offset:3072
	ds_read_b128 v[178:181], v247 offset:4096
	ds_read_b128 v[182:185], v247 offset:5120
	ds_read_b128 v[186:189], v247 offset:6144
	ds_read_b128 v[190:193], v247 offset:7168
	global_load_lds_dwordx4 v[210:211], off
	v_lshl_add_u64 v[210:211], s[48:49], 0, v[208:209]
	s_add_i32 m0, s92, 0xe000
	s_nop 0
	global_load_lds_dwordx4 v[210:211], off
	s_waitcnt vmcnt(8)
	s_waitcnt lgkmcnt(0)
	s_barrier
	s_setprio 1
	v_mfma_f32_16x16x32_bf16 v[130:133], v[110:113], v[162:165], v[130:133]
	v_mfma_f32_16x16x32_bf16 v[130:133], v[118:121], v[166:169], v[130:133]
	v_mfma_f32_16x16x32_bf16 v[114:117], v[118:121], v[174:177], v[114:117]
	v_mfma_f32_16x16x32_bf16 v[114:117], v[110:113], v[170:173], v[114:117]
	v_mfma_f32_16x16x32_bf16 v[94:97], v[110:113], v[178:181], v[94:97]
	v_mfma_f32_16x16x32_bf16 v[94:97], v[118:121], v[182:185], v[94:97]
	v_mfma_f32_16x16x32_bf16 v[78:81], v[118:121], v[190:193], v[78:81]
	v_mfma_f32_16x16x32_bf16 v[78:81], v[110:113], v[186:189], v[78:81]
	v_mfma_f32_16x16x32_bf16 v[134:137], v[138:141], v[162:165], v[134:137]
	v_mfma_f32_16x16x32_bf16 v[134:137], v[142:145], v[166:169], v[134:137]
	v_mfma_f32_16x16x32_bf16 v[106:109], v[142:145], v[174:177], v[106:109]
	v_mfma_f32_16x16x32_bf16 v[106:109], v[138:141], v[170:173], v[106:109]
	v_mfma_f32_16x16x32_bf16 v[90:93], v[138:141], v[178:181], v[90:93]
	v_mfma_f32_16x16x32_bf16 v[90:93], v[142:145], v[182:185], v[90:93]
	v_mfma_f32_16x16x32_bf16 v[74:77], v[142:145], v[190:193], v[74:77]
	v_mfma_f32_16x16x32_bf16 v[74:77], v[138:141], v[186:189], v[74:77]
	v_mfma_f32_16x16x32_bf16 v[126:129], v[146:149], v[162:165], v[126:129]
	v_mfma_f32_16x16x32_bf16 v[126:129], v[150:153], v[166:169], v[126:129]
	v_mfma_f32_16x16x32_bf16 v[102:105], v[150:153], v[174:177], v[102:105]
	v_mfma_f32_16x16x32_bf16 v[102:105], v[146:149], v[170:173], v[102:105]
	v_mfma_f32_16x16x32_bf16 v[86:89], v[146:149], v[178:181], v[86:89]
	v_mfma_f32_16x16x32_bf16 v[86:89], v[150:153], v[182:185], v[86:89]
	v_mfma_f32_16x16x32_bf16 v[70:73], v[150:153], v[190:193], v[70:73]
	v_mfma_f32_16x16x32_bf16 v[70:73], v[146:149], v[186:189], v[70:73]
	v_mfma_f32_16x16x32_bf16 v[122:125], v[154:157], v[162:165], v[122:125]
	v_mfma_f32_16x16x32_bf16 v[122:125], v[158:161], v[166:169], v[122:125]
	v_mfma_f32_16x16x32_bf16 v[98:101], v[158:161], v[174:177], v[98:101]
	v_mfma_f32_16x16x32_bf16 v[98:101], v[154:157], v[170:173], v[98:101]
	v_mfma_f32_16x16x32_bf16 v[82:85], v[154:157], v[178:181], v[82:85]
	v_mfma_f32_16x16x32_bf16 v[82:85], v[158:161], v[182:185], v[82:85]
	v_mfma_f32_16x16x32_bf16 v[66:69], v[158:161], v[190:193], v[66:69]
	v_mfma_f32_16x16x32_bf16 v[66:69], v[154:157], v[186:189], v[66:69]
	s_setprio 0
	s_barrier
	s_add_i32 vcc_hi, vcc_hi, s6
	v_lshl_add_u64 v[210:211], s[38:39], 0, v[0:1]
	s_mov_b32 m0, vcc_hi
	ds_read_b128 v[162:165], v247 offset:16384
	ds_read_b128 v[166:169], v247 offset:17408
	ds_read_b128 v[170:173], v247 offset:18432
	ds_read_b128 v[174:177], v247 offset:19456
	ds_read_b128 v[178:181], v247 offset:20480
	ds_read_b128 v[182:185], v247 offset:21504
	ds_read_b128 v[186:189], v247 offset:22528
	ds_read_b128 v[190:193], v247 offset:23552
	global_load_lds_dwordx4 v[210:211], off
	s_add_i32 m0, vcc_hi, 0x2000
	v_lshl_add_u64 v[212:213], s[38:39], 0, v[204:205]
	s_add_u32 s38, s38, s58
	s_addc_u32 s39, s39, 0
	s_add_i32 s18, s18, s6
	global_load_lds_dwordx4 v[212:213], off
	v_lshl_add_u64 v[214:215], s[38:39], 0, v[0:1]
	s_mov_b32 m0, s18
	v_lshl_add_u64 v[216:217], s[38:39], 0, v[204:205]
	global_load_lds_dwordx4 v[214:215], off
	s_add_i32 m0, s18, 0x2000
	v_lshl_add_u64 v[218:219], s[46:47], 0, v[194:195]
	global_load_lds_dwordx4 v[216:217], off
	s_mov_b32 m0, s92
	v_lshl_add_u64 v[220:221], s[46:47], 0, v[202:203]
	global_load_lds_dwordx4 v[218:219], off
	s_mov_b32 m0, s93
	s_nop 0
	global_load_lds_dwordx4 v[220:221], off
	s_waitcnt vmcnt(8)
	s_waitcnt lgkmcnt(0)
	s_barrier
; #define PG8_STAGE(bufoff, gbase, voff) do { _Pragma("unroll") for (int _i = 0; _i < 2; ++_i) \
;         __builtin_amdgcn_global_load_lds((const unsigned*)((const char*)(gbase) + (voff)[_i]), (PG8_LAS unsigned*)(lds + (bufoff) + ldsw + _i * 8192), 16, 0, 0); } while (0)
; #define PG8_LDA(dst, b, h) do { _Pragma("unroll") for (int m = 0; m < 4; ++m) _Pragma("unroll") for (int k = 0; k < 2; ++k) dst[m][k] = *(const PG8_LAS bf16x8*)(lds + PG8_SA(b, h) + aoff + m * 2048 + k * 1024); } while (0)
; #define PG8_LDB(dst, b, h) do { _Pragma("unroll") for (int n = 0; n < 2; ++n) _Pragma("unroll") for (int k = 0; k < 2; ++k) dst[n][k] = *(const PG8_LAS bf16x8*)(lds + PG8_SB(b, h) + boff + n * 2048 + k * 1024); } while (0)
; #define PG8_MMA(ai, bj, At, Bt) do { __builtin_amdgcn_s_setprio(1); _Pragma("unroll") for (int m = 0; m < 4; ++m) _Pragma("unroll") for (int n = 0; n < 2; ++n) _Pragma("unroll") for (int k = 0; k < 2; ++k) \
;         acc[ai][bj][m][n] = __builtin_amdgcn_mfma_f32_16x16x32_bf16(Bt[n][k], At[m][k], acc[ai][bj][m][n], 0, 0, 0); __builtin_amdgcn_s_setprio(0); } while (0)
; #define PG8_WAIT_V(n) asm volatile("s_waitcnt vmcnt(" #n ")" ::: "memory")
; #define PG8_WAIT_L(n) asm volatile("s_waitcnt lgkmcnt(" #n ")" ::: "memory")
; #define PG8_BAR __builtin_amdgcn_s_barrier()
; #define PG8_SCHED __builtin_amdgcn_sched_barrier(0)
; template <class Epi, class Sched, bool ALIGN_EPI = false, bool SP2 = false>
; __device__ __forceinline__ void gemm_phase(PG8_LAS unsigned char* lds, const Gemm g, const Sched& S, const Epi& E) {
;     ...
;             PG8_WAIT_V(8); PG8_WAIT_L(0); PG8_BAR; PG8_MMA(1, 0, At, B0); PG8_MMA(1, 1, At, B1); PG8_BAR; PG8_SCHED;
;             PG8_LDB(B0, 1, 0); PG8_LDB(B1, 1, 1); PG8_SCHED; PG8_LDA(At, 1, 0); PG8_STAGE(PG8_SA(0, 1), a2 + hstep, voffA);
;             PG8_WAIT_V(8); PG8_WAIT_L(0); PG8_BAR; PG8_MMA(0, 0, At, B0); PG8_MMA(0, 1, At, B1); PG8_BAR; PG8_SCHED;
	s_setprio 1
	v_mfma_f32_16x16x32_bf16 v[62:65], v[110:113], v[162:165], v[62:65]
	v_mfma_f32_16x16x32_bf16 v[62:65], v[118:121], v[166:169], v[62:65]
	v_mfma_f32_16x16x32_bf16 v[46:49], v[118:121], v[174:177], v[46:49]
	v_mfma_f32_16x16x32_bf16 v[46:49], v[110:113], v[170:173], v[46:49]
	v_mfma_f32_16x16x32_bf16 v[30:33], v[110:113], v[178:181], v[30:33]
	v_mfma_f32_16x16x32_bf16 v[30:33], v[118:121], v[182:185], v[30:33]
	v_mfma_f32_16x16x32_bf16 v[14:17], v[118:121], v[190:193], v[14:17]
	v_mfma_f32_16x16x32_bf16 v[14:17], v[110:113], v[186:189], v[14:17]
	v_mfma_f32_16x16x32_bf16 v[58:61], v[138:141], v[162:165], v[58:61]
	v_mfma_f32_16x16x32_bf16 v[58:61], v[142:145], v[166:169], v[58:61]
	v_mfma_f32_16x16x32_bf16 v[42:45], v[142:145], v[174:177], v[42:45]
	v_mfma_f32_16x16x32_bf16 v[42:45], v[138:141], v[170:173], v[42:45]
	v_mfma_f32_16x16x32_bf16 v[26:29], v[138:141], v[178:181], v[26:29]
	v_mfma_f32_16x16x32_bf16 v[26:29], v[142:145], v[182:185], v[26:29]
	v_mfma_f32_16x16x32_bf16 v[10:13], v[142:145], v[190:193], v[10:13]
	v_mfma_f32_16x16x32_bf16 v[10:13], v[138:141], v[186:189], v[10:13]
	v_mfma_f32_16x16x32_bf16 v[54:57], v[146:149], v[162:165], v[54:57]
	v_mfma_f32_16x16x32_bf16 v[54:57], v[150:153], v[166:169], v[54:57]
	v_mfma_f32_16x16x32_bf16 v[38:41], v[150:153], v[174:177], v[38:41]
	v_mfma_f32_16x16x32_bf16 v[38:41], v[146:149], v[170:173], v[38:41]
	v_mfma_f32_16x16x32_bf16 v[22:25], v[146:149], v[178:181], v[22:25]
	v_mfma_f32_16x16x32_bf16 v[22:25], v[150:153], v[182:185], v[22:25]
	v_mfma_f32_16x16x32_bf16 v[6:9], v[150:153], v[190:193], v[6:9]
	v_mfma_f32_16x16x32_bf16 v[6:9], v[146:149], v[186:189], v[6:9]
	v_mfma_f32_16x16x32_bf16 v[50:53], v[154:157], v[162:165], v[50:53]
	v_mfma_f32_16x16x32_bf16 v[50:53], v[158:161], v[166:169], v[50:53]
	v_mfma_f32_16x16x32_bf16 v[34:37], v[158:161], v[174:177], v[34:37]
	v_mfma_f32_16x16x32_bf16 v[34:37], v[154:157], v[170:173], v[34:37]
	v_mfma_f32_16x16x32_bf16 v[18:21], v[154:157], v[178:181], v[18:21]
	v_mfma_f32_16x16x32_bf16 v[18:21], v[158:161], v[182:185], v[18:21]
	v_mfma_f32_16x16x32_bf16 v[2:5], v[158:161], v[190:193], v[2:5]
	v_mfma_f32_16x16x32_bf16 v[2:5], v[154:157], v[186:189], v[2:5]
	s_setprio 0
	s_barrier
	s_add_i32 s18, 0, 0x18000
	s_add_i32 vcc_hi, 0, 0x1c000
	v_add_u32_e32 v142, s18, v245
	v_add_u32_e32 v158, vcc_hi, v245
	ds_read_b128 v[110:113], v142
	ds_read_b128 v[118:121], v142 offset:1024
	ds_read_b128 v[138:141], v142 offset:2048
	ds_read_b128 v[142:145], v142 offset:3072
	ds_read_b128 v[146:149], v158
	ds_read_b128 v[150:153], v158 offset:1024
	ds_read_b128 v[154:157], v158 offset:2048
	ds_read_b128 v[158:161], v158 offset:3072
	s_add_u32 s38, s46, s58
	s_addc_u32 s39, s47, 0
	s_mov_b32 m0, s94
	v_lshl_add_u64 v[222:223], s[38:39], 0, v[194:195]
	ds_read_b128 v[162:165], v247 offset:32768
	ds_read_b128 v[166:169], v247 offset:33792
	ds_read_b128 v[170:173], v247 offset:34816
	ds_read_b128 v[174:177], v247 offset:35840
	ds_read_b128 v[178:181], v247 offset:36864
	ds_read_b128 v[182:185], v247 offset:37888
	ds_read_b128 v[186:189], v247 offset:38912
	ds_read_b128 v[190:193], v247 offset:39936
	global_load_lds_dwordx4 v[222:223], off
	v_lshl_add_u64 v[222:223], s[38:39], 0, v[202:203]
	s_mov_b32 m0, s95
	s_nop 0
	global_load_lds_dwordx4 v[222:223], off
	s_waitcnt vmcnt(8)
	s_waitcnt lgkmcnt(0)
	s_barrier
	s_setprio 1
	v_mfma_f32_16x16x32_bf16 v[130:133], v[110:113], v[162:165], v[130:133]
	v_mfma_f32_16x16x32_bf16 v[130:133], v[118:121], v[166:169], v[130:133]
	v_mfma_f32_16x16x32_bf16 v[114:117], v[118:121], v[174:177], v[114:117]
	v_mfma_f32_16x16x32_bf16 v[114:117], v[110:113], v[170:173], v[114:117]
	v_mfma_f32_16x16x32_bf16 v[94:97], v[110:113], v[178:181], v[94:97]
	v_mfma_f32_16x16x32_bf16 v[94:97], v[118:121], v[182:185], v[94:97]
	v_mfma_f32_16x16x32_bf16 v[78:81], v[118:121], v[190:193], v[78:81]
	v_mfma_f32_16x16x32_bf16 v[78:81], v[110:113], v[186:189], v[78:81]
	v_mfma_f32_16x16x32_bf16 v[134:137], v[138:141], v[162:165], v[134:137]
	v_mfma_f32_16x16x32_bf16 v[134:137], v[142:145], v[166:169], v[134:137]
	v_mfma_f32_16x16x32_bf16 v[106:109], v[142:145], v[174:177], v[106:109]
	v_mfma_f32_16x16x32_bf16 v[106:109], v[138:141], v[170:173], v[106:109]
	v_mfma_f32_16x16x32_bf16 v[90:93], v[138:141], v[178:181], v[90:93]
	v_mfma_f32_16x16x32_bf16 v[90:93], v[142:145], v[182:185], v[90:93]
	v_mfma_f32_16x16x32_bf16 v[74:77], v[142:145], v[190:193], v[74:77]
	v_mfma_f32_16x16x32_bf16 v[74:77], v[138:141], v[186:189], v[74:77]
	v_mfma_f32_16x16x32_bf16 v[126:129], v[146:149], v[162:165], v[126:129]
	v_mfma_f32_16x16x32_bf16 v[126:129], v[150:153], v[166:169], v[126:129]
	v_mfma_f32_16x16x32_bf16 v[102:105], v[150:153], v[174:177], v[102:105]
	v_mfma_f32_16x16x32_bf16 v[102:105], v[146:149], v[170:173], v[102:105]
	v_mfma_f32_16x16x32_bf16 v[86:89], v[146:149], v[178:181], v[86:89]
	v_mfma_f32_16x16x32_bf16 v[86:89], v[150:153], v[182:185], v[86:89]
	v_mfma_f32_16x16x32_bf16 v[70:73], v[150:153], v[190:193], v[70:73]
	v_mfma_f32_16x16x32_bf16 v[70:73], v[146:149], v[186:189], v[70:73]
	v_mfma_f32_16x16x32_bf16 v[122:125], v[154:157], v[162:165], v[122:125]
	v_mfma_f32_16x16x32_bf16 v[122:125], v[158:161], v[166:169], v[122:125]
	v_mfma_f32_16x16x32_bf16 v[98:101], v[158:161], v[174:177], v[98:101]
	v_mfma_f32_16x16x32_bf16 v[98:101], v[154:157], v[170:173], v[98:101]
	v_mfma_f32_16x16x32_bf16 v[82:85], v[154:157], v[178:181], v[82:85]
	v_mfma_f32_16x16x32_bf16 v[82:85], v[158:161], v[182:185], v[82:85]
	v_mfma_f32_16x16x32_bf16 v[66:69], v[158:161], v[190:193], v[66:69]
	v_mfma_f32_16x16x32_bf16 v[66:69], v[154:157], v[186:189], v[66:69]
	s_setprio 0
	s_barrier
; #define PG8_STAGE(bufoff, gbase, voff) do { _Pragma("unroll") for (int _i = 0; _i < 2; ++_i) \
;         __builtin_amdgcn_global_load_lds((const unsigned*)((const char*)(gbase) + (voff)[_i]), (PG8_LAS unsigned*)(lds + (bufoff) + ldsw + _i * 8192), 16, 0, 0); } while (0)
; #define PG8_LDA(dst, b, h) do { _Pragma("unroll") for (int m = 0; m < 4; ++m) _Pragma("unroll") for (int k = 0; k < 2; ++k) dst[m][k] = *(const PG8_LAS bf16x8*)(lds + PG8_SA(b, h) + aoff + m * 2048 + k * 1024); } while (0)
; #define PG8_WAIT_V(n) asm volatile("s_waitcnt vmcnt(" #n ")" ::: "memory")
; template <class Epi, class Sched, bool ALIGN_EPI = false, bool SP2 = false>
; __device__ __forceinline__ void gemm_phase(PG8_LAS unsigned char* lds, const Gemm g, const Sched& S, const Epi& E) {
;     ...
;             PG8_LDA(At, 1, 1); PG8_STAGE(PG8_SB(1, 0), b3, voffB); PG8_STAGE(PG8_SB(1, 1), b3 + hstep, voffB); PG8_STAGE(PG8_SA(1, 0), a3, voffA);
;             PG8_WAIT_V(8); PG8_WAIT_L(0); PG8_BAR; PG8_MMA(1, 0, At, B0); PG8_MMA(1, 1, At, B1); PG8_BAR; PG8_SCHED;
;             } else {
;             PG8_LDB(B0, 0, 0); PG8_SCHED; PG8_LDA(At, 0, 0); PG8_STAGE(PG8_SA(1, 1), a1 + hstep, voffA);
;             PG8_WAIT_L(8); PG8_BAR; PG8_WAIT_L(0); PG8_MMA(0, 0, At, B0); PG8_BAR; PG8_SCHED;
;             PG8_LDB(B1, 0, 1); PG8_STAGE(PG8_SB(0, 0), b2, voffB);
;             PG8_BAR; PG8_WAIT_L(0); PG8_MMA(0, 1, At, B1); PG8_BAR;
;             PG8_LDA(At, 0, 1); PG8_STAGE(PG8_SA(0, 0), a2, voffA);
;             PG8_BAR; PG8_WAIT_L(0); PG8_MMA(1, 0, At, B0); PG8_BAR; PG8_SCHED;
;             PG8_STAGE(PG8_SB(0, 1), b2 + hstep, voffB);
;             PG8_WAIT_V(6); PG8_BAR; PG8_MMA(1, 1, At, B1); PG8_BAR;
;             PG8_LDB(B0, 1, 0); PG8_SCHED; PG8_LDA(At, 1, 0); PG8_STAGE(PG8_SA(0, 1), a2 + hstep, voffA);
;             PG8_WAIT_L(8); PG8_BAR; PG8_WAIT_L(0); PG8_MMA(0, 0, At, B0); PG8_BAR; PG8_SCHED;
;             PG8_LDB(B1, 1, 1); PG8_STAGE(PG8_SB(1, 0), b3, voffB);
;             PG8_BAR; PG8_WAIT_L(0); PG8_MMA(0, 1, At, B1); PG8_BAR;
;             PG8_LDA(At, 1, 1); PG8_STAGE(PG8_SA(1, 0), a3, voffA);
;             PG8_BAR; PG8_WAIT_L(0); PG8_MMA(1, 0, At, B0); PG8_BAR; PG8_SCHED;
;             PG8_STAGE(PG8_SB(1, 1), b3 + hstep, voffB);
;             PG8_WAIT_V(6); PG8_BAR; PG8_MMA(1, 1, At, B1); PG8_BAR;
;             }
;         }
;         if constexpr (ALIGN_EPI) { if (wr == 0) PG8_BAR; }
	s_add_i32 s18, s18, s6
	v_lshl_add_u64 v[210:211], v[210:211], 0, s[30:31]
	s_mov_b32 m0, s18
	ds_read_b128 v[162:165], v247 offset:49152
	ds_read_b128 v[166:169], v247 offset:50176
	ds_read_b128 v[170:173], v247 offset:51200
	ds_read_b128 v[174:177], v247 offset:52224
	ds_read_b128 v[178:181], v247 offset:53248
	ds_read_b128 v[182:185], v247 offset:54272
	ds_read_b128 v[186:189], v247 offset:55296
	ds_read_b128 v[190:193], v247 offset:56320
	global_load_lds_dwordx4 v[210:211], off
	v_lshl_add_u64 v[210:211], v[212:213], 0, s[30:31]
	s_add_i32 m0, s18, 0x2000
	s_add_i32 s18, vcc_hi, s6
	global_load_lds_dwordx4 v[210:211], off
	v_lshl_add_u64 v[210:211], v[214:215], 0, s[30:31]
	s_mov_b32 m0, s18
	s_nop 0
	global_load_lds_dwordx4 v[210:211], off
	v_lshl_add_u64 v[210:211], v[216:217], 0, s[30:31]
	s_add_i32 m0, s18, 0x2000
	s_nop 0
	global_load_lds_dwordx4 v[210:211], off
	v_lshl_add_u64 v[210:211], v[218:219], 0, s[30:31]
	s_mov_b32 m0, s97
	s_nop 0
	global_load_lds_dwordx4 v[210:211], off
	v_lshl_add_u64 v[210:211], v[220:221], 0, s[30:31]
	s_mov_b32 m0, s98
	s_nop 0
	global_load_lds_dwordx4 v[210:211], off
	s_waitcnt vmcnt(8)
	s_waitcnt lgkmcnt(0)
	s_barrier
	s_setprio 1
	v_mfma_f32_16x16x32_bf16 v[62:65], v[110:113], v[162:165], v[62:65]
	v_mfma_f32_16x16x32_bf16 v[62:65], v[118:121], v[166:169], v[62:65]
	v_mfma_f32_16x16x32_bf16 v[46:49], v[118:121], v[174:177], v[46:49]
	v_mfma_f32_16x16x32_bf16 v[46:49], v[110:113], v[170:173], v[46:49]
	v_mfma_f32_16x16x32_bf16 v[30:33], v[110:113], v[178:181], v[30:33]
	v_mfma_f32_16x16x32_bf16 v[30:33], v[118:121], v[182:185], v[30:33]
	v_mfma_f32_16x16x32_bf16 v[14:17], v[118:121], v[190:193], v[14:17]
	v_mfma_f32_16x16x32_bf16 v[14:17], v[110:113], v[186:189], v[14:17]
	v_mfma_f32_16x16x32_bf16 v[58:61], v[138:141], v[162:165], v[58:61]
	v_mfma_f32_16x16x32_bf16 v[58:61], v[142:145], v[166:169], v[58:61]
	v_mfma_f32_16x16x32_bf16 v[42:45], v[142:145], v[174:177], v[42:45]
	v_mfma_f32_16x16x32_bf16 v[42:45], v[138:141], v[170:173], v[42:45]
	v_mfma_f32_16x16x32_bf16 v[26:29], v[138:141], v[178:181], v[26:29]
	v_mfma_f32_16x16x32_bf16 v[26:29], v[142:145], v[182:185], v[26:29]
	v_mfma_f32_16x16x32_bf16 v[10:13], v[142:145], v[190:193], v[10:13]
	v_mfma_f32_16x16x32_bf16 v[10:13], v[138:141], v[186:189], v[10:13]
	v_mfma_f32_16x16x32_bf16 v[54:57], v[146:149], v[162:165], v[54:57]
	v_mfma_f32_16x16x32_bf16 v[54:57], v[150:153], v[166:169], v[54:57]
	v_mfma_f32_16x16x32_bf16 v[38:41], v[150:153], v[174:177], v[38:41]
	v_mfma_f32_16x16x32_bf16 v[38:41], v[146:149], v[170:173], v[38:41]
	v_mfma_f32_16x16x32_bf16 v[22:25], v[146:149], v[178:181], v[22:25]
	v_mfma_f32_16x16x32_bf16 v[22:25], v[150:153], v[182:185], v[22:25]
	v_mfma_f32_16x16x32_bf16 v[6:9], v[150:153], v[190:193], v[6:9]
	v_mfma_f32_16x16x32_bf16 v[6:9], v[146:149], v[186:189], v[6:9]
	v_mfma_f32_16x16x32_bf16 v[50:53], v[154:157], v[162:165], v[50:53]
	v_mfma_f32_16x16x32_bf16 v[50:53], v[158:161], v[166:169], v[50:53]
	v_mfma_f32_16x16x32_bf16 v[34:37], v[158:161], v[174:177], v[34:37]
	v_mfma_f32_16x16x32_bf16 v[34:37], v[154:157], v[170:173], v[34:37]
	v_mfma_f32_16x16x32_bf16 v[18:21], v[154:157], v[178:181], v[18:21]
	v_mfma_f32_16x16x32_bf16 v[18:21], v[158:161], v[182:185], v[18:21]
	v_mfma_f32_16x16x32_bf16 v[2:5], v[158:161], v[190:193], v[2:5]
	v_mfma_f32_16x16x32_bf16 v[2:5], v[154:157], v[186:189], v[2:5]
	s_setprio 0
	s_barrier
	s_add_u32 s48, s48, 0x100
	s_addc_u32 s49, s49, 0
	s_add_u32 s50, s50, 0x100
	s_addc_u32 s51, s51, 0
	s_cmp_ge_u32 vcc_lo, s96
	s_mov_b32 s46, vcc_lo
	s_cbranch_scc0 .LBB0_274
	s_and_b64 vcc, exec, s[72:73]
	s_cbranch_vccz .LBB0_277
	s_barrier

; #define PG8_STAGE(bufoff, gbase, voff) do { _Pragma("unroll") for (int _i = 0; _i < 2; ++_i) \
;         __builtin_amdgcn_global_load_lds((const unsigned*)((const char*)(gbase) + (voff)[_i]), (PG8_LAS unsigned*)(lds + (bufoff) + ldsw + _i * 8192), 16, 0, 0); } while (0)
; #define PG8_LDA(dst, b, h) do { _Pragma("unroll") for (int m = 0; m < 4; ++m) _Pragma("unroll") for (int k = 0; k < 2; ++k) dst[m][k] = *(const PG8_LAS bf16x8*)(lds + PG8_SA(b, h) + aoff + m * 2048 + k * 1024); } while (0)
; #define PG8_LDB(dst, b, h) do { _Pragma("unroll") for (int n = 0; n < 2; ++n) _Pragma("unroll") for (int k = 0; k < 2; ++k) dst[n][k] = *(const PG8_LAS bf16x8*)(lds + PG8_SB(b, h) + boff + n * 2048 + k * 1024); } while (0)
; #define PG8_MMA(ai, bj, At, Bt) do { __builtin_amdgcn_s_setprio(1); _Pragma("unroll") for (int m = 0; m < 4; ++m) _Pragma("unroll") for (int n = 0; n < 2; ++n) _Pragma("unroll") for (int k = 0; k < 2; ++k) \
;         acc[ai][bj][m][n] = __builtin_amdgcn_mfma_f32_16x16x32_bf16(Bt[n][k], At[m][k], acc[ai][bj][m][n], 0, 0, 0); __builtin_amdgcn_s_setprio(0); } while (0)
; #define PG8_WAIT_V(n) asm volatile("s_waitcnt vmcnt(" #n ")" ::: "memory")
; #define PG8_WAIT_L(n) asm volatile("s_waitcnt lgkmcnt(" #n ")" ::: "memory")
; template <class Epi, class Sched, bool ALIGN_EPI = false, bool SP2 = false>
; __device__ __forceinline__ void gemm_phase(PG8_LAS unsigned char* lds, const Gemm g, const Sched& S, const Epi& E) {
;     ...
;             const bool last = (t == nt - 2);
;             const char* a1 = cA + (size_t)(t + 1) * kstep;
;             const char* a2 = last ? nA : cA + (size_t)(t + 2) * kstep; const char* b2 = last ? nB : cB + (size_t)(t + 2) * kstep;
;             const char* a3 = a2 + kstep; const char* b3 = b2 + kstep;
;             if (last && has_next) S.a_ready(nxt);
;             if constexpr (SP2) {
;             PG8_LDB(B0, 0, 0); PG8_LDB(B1, 0, 1); PG8_SCHED; PG8_LDA(At, 0, 0); PG8_STAGE(PG8_SA(1, 1), a1 + hstep, voffA);
;             PG8_WAIT_V(8); PG8_WAIT_L(0); PG8_BAR; PG8_MMA(0, 0, At, B0); PG8_MMA(0, 1, At, B1); PG8_BAR; PG8_SCHED;
;             PG8_LDA(At, 0, 1); PG8_STAGE(PG8_SB(0, 0), b2, voffB); PG8_STAGE(PG8_SB(0, 1), b2 + hstep, voffB); PG8_STAGE(PG8_SA(0, 0), a2, voffA);
;             PG8_WAIT_V(8); PG8_WAIT_L(0); PG8_BAR; PG8_MMA(1, 0, At, B0); PG8_MMA(1, 1, At, B1); PG8_BAR; PG8_SCHED;
.LBB0_408:
	s_add_u32 s38, s48, 0xfffc0080
	s_addc_u32 s39, s49, -1
	s_add_i32 s85, 0, 0x10000
	s_cmp_eq_u32 s84, 12
	s_cselect_b32 s73, s21, s39
	s_cselect_b32 s72, s27, s38
	v_add_u32_e32 v0, s85, v167
	s_cselect_b32 s47, s29, s69
	s_cselect_b32 s46, s33, s53
	s_add_i32 s38, 0, 0x14000
	ds_read_b128 v[142:145], v0
	ds_read_b128 v[146:149], v0 offset:1024
	ds_read_b128 v[150:153], v0 offset:2048
	ds_read_b128 v[154:157], v0 offset:3072
	v_add_u32_e32 v0, s38, v167
	ds_read_b128 v[158:161], v0
	ds_read_b128 v[162:165], v0 offset:1024
	ds_read_b128 v[172:175], v0 offset:2048
	ds_read_b128 v[176:179], v0 offset:3072
	v_lshl_add_u64 v[218:219], s[48:49], 0, v[138:139]
	s_add_i32 m0, s76, 0xc000
	ds_read_b128 v[180:183], v170
	ds_read_b128 v[184:187], v170 offset:1024
	ds_read_b128 v[188:191], v170 offset:2048
	ds_read_b128 v[192:195], v170 offset:3072
	ds_read_b128 v[202:205], v170 offset:4096
	ds_read_b128 v[206:209], v170 offset:5120
	ds_read_b128 v[210:213], v170 offset:6144
	ds_read_b128 v[214:217], v170 offset:7168
	global_load_lds_dwordx4 v[218:219], off
	v_lshl_add_u64 v[218:219], s[48:49], 0, v[140:141]
	s_add_i32 m0, s76, 0xe000
	s_nop 0
	global_load_lds_dwordx4 v[218:219], off
	s_waitcnt vmcnt(8)
	s_waitcnt lgkmcnt(0)
	s_barrier
	s_setprio 1
	v_mfma_f32_16x16x32_bf16 v[122:125], v[142:145], v[180:183], v[122:125]
	v_mfma_f32_16x16x32_bf16 v[122:125], v[146:149], v[184:187], v[122:125]
	v_mfma_f32_16x16x32_bf16 v[106:109], v[146:149], v[192:195], v[106:109]
	v_mfma_f32_16x16x32_bf16 v[106:109], v[142:145], v[188:191], v[106:109]
	v_mfma_f32_16x16x32_bf16 v[90:93], v[142:145], v[202:205], v[90:93]
	v_mfma_f32_16x16x32_bf16 v[90:93], v[146:149], v[206:209], v[90:93]
	v_mfma_f32_16x16x32_bf16 v[74:77], v[146:149], v[214:217], v[74:77]
	v_mfma_f32_16x16x32_bf16 v[74:77], v[142:145], v[210:213], v[74:77]
	v_mfma_f32_16x16x32_bf16 v[126:129], v[150:153], v[180:183], v[126:129]
	v_mfma_f32_16x16x32_bf16 v[126:129], v[154:157], v[184:187], v[126:129]
	v_mfma_f32_16x16x32_bf16 v[110:113], v[154:157], v[192:195], v[110:113]
	v_mfma_f32_16x16x32_bf16 v[110:113], v[150:153], v[188:191], v[110:113]
	v_mfma_f32_16x16x32_bf16 v[94:97], v[150:153], v[202:205], v[94:97]
	v_mfma_f32_16x16x32_bf16 v[94:97], v[154:157], v[206:209], v[94:97]
	v_mfma_f32_16x16x32_bf16 v[78:81], v[154:157], v[214:217], v[78:81]
	v_mfma_f32_16x16x32_bf16 v[78:81], v[150:153], v[210:213], v[78:81]
	v_mfma_f32_16x16x32_bf16 v[114:117], v[158:161], v[180:183], v[114:117]
	v_mfma_f32_16x16x32_bf16 v[114:117], v[162:165], v[184:187], v[114:117]
	v_mfma_f32_16x16x32_bf16 v[98:101], v[162:165], v[192:195], v[98:101]
	v_mfma_f32_16x16x32_bf16 v[98:101], v[158:161], v[188:191], v[98:101]
	v_mfma_f32_16x16x32_bf16 v[82:85], v[158:161], v[202:205], v[82:85]
	v_mfma_f32_16x16x32_bf16 v[82:85], v[162:165], v[206:209], v[82:85]
	v_mfma_f32_16x16x32_bf16 v[66:69], v[162:165], v[214:217], v[66:69]
	v_mfma_f32_16x16x32_bf16 v[66:69], v[158:161], v[210:213], v[66:69]
	v_mfma_f32_16x16x32_bf16 v[118:121], v[172:175], v[180:183], v[118:121]
	v_mfma_f32_16x16x32_bf16 v[118:121], v[176:179], v[184:187], v[118:121]
	v_mfma_f32_16x16x32_bf16 v[102:105], v[176:179], v[192:195], v[102:105]
	v_mfma_f32_16x16x32_bf16 v[102:105], v[172:175], v[188:191], v[102:105]
	v_mfma_f32_16x16x32_bf16 v[86:89], v[172:175], v[202:205], v[86:89]
	v_mfma_f32_16x16x32_bf16 v[86:89], v[176:179], v[206:209], v[86:89]
	v_mfma_f32_16x16x32_bf16 v[70:73], v[176:179], v[214:217], v[70:73]
	v_mfma_f32_16x16x32_bf16 v[70:73], v[172:175], v[210:213], v[70:73]
	s_setprio 0
	s_barrier
	s_add_i32 s39, s85, s75
	v_lshl_add_u64 v[218:219], s[46:47], 0, v[134:135]
	s_mov_b32 m0, s39
	ds_read_b128 v[180:183], v170 offset:16384
	ds_read_b128 v[184:187], v170 offset:17408
	ds_read_b128 v[188:191], v170 offset:18432
	ds_read_b128 v[192:195], v170 offset:19456
	ds_read_b128 v[202:205], v170 offset:20480
	ds_read_b128 v[206:209], v170 offset:21504
	ds_read_b128 v[210:213], v170 offset:22528
	ds_read_b128 v[214:217], v170 offset:23552
	global_load_lds_dwordx4 v[218:219], off
	s_add_i32 m0, s39, 0x2000
	s_add_u32 s92, s46, 0x40000
	v_lshl_add_u64 v[220:221], s[46:47], 0, v[130:131]
	s_addc_u32 s93, s47, 0
	s_add_i32 s38, s38, s75
	global_load_lds_dwordx4 v[220:221], off
	v_lshl_add_u64 v[222:223], s[92:93], 0, v[134:135]
	s_mov_b32 m0, s38
	v_lshl_add_u64 v[224:225], s[72:73], 0, v[132:133]
	global_load_lds_dwordx4 v[222:223], off
	v_lshl_add_u64 v[222:223], s[92:93], 0, v[130:131]
	s_add_i32 m0, s38, 0x2000
	s_nop 0
	global_load_lds_dwordx4 v[222:223], off
	v_lshl_add_u64 v[222:223], s[72:73], 0, v[136:137]
	s_mov_b32 m0, s76
	s_nop 0
	global_load_lds_dwordx4 v[222:223], off
	s_mov_b32 m0, s77
	s_nop 0
	global_load_lds_dwordx4 v[224:225], off
	s_waitcnt vmcnt(8)
	s_waitcnt lgkmcnt(0)
	s_barrier
; #define PG8_STAGE(bufoff, gbase, voff) do { _Pragma("unroll") for (int _i = 0; _i < 2; ++_i) \
;         __builtin_amdgcn_global_load_lds((const unsigned*)((const char*)(gbase) + (voff)[_i]), (PG8_LAS unsigned*)(lds + (bufoff) + ldsw + _i * 8192), 16, 0, 0); } while (0)
; #define PG8_LDA(dst, b, h) do { _Pragma("unroll") for (int m = 0; m < 4; ++m) _Pragma("unroll") for (int k = 0; k < 2; ++k) dst[m][k] = *(const PG8_LAS bf16x8*)(lds + PG8_SA(b, h) + aoff + m * 2048 + k * 1024); } while (0)
; #define PG8_LDB(dst, b, h) do { _Pragma("unroll") for (int n = 0; n < 2; ++n) _Pragma("unroll") for (int k = 0; k < 2; ++k) dst[n][k] = *(const PG8_LAS bf16x8*)(lds + PG8_SB(b, h) + boff + n * 2048 + k * 1024); } while (0)
; #define PG8_MMA(ai, bj, At, Bt) do { __builtin_amdgcn_s_setprio(1); _Pragma("unroll") for (int m = 0; m < 4; ++m) _Pragma("unroll") for (int n = 0; n < 2; ++n) _Pragma("unroll") for (int k = 0; k < 2; ++k) \
;         acc[ai][bj][m][n] = __builtin_amdgcn_mfma_f32_16x16x32_bf16(Bt[n][k], At[m][k], acc[ai][bj][m][n], 0, 0, 0); __builtin_amdgcn_s_setprio(0); } while (0)
; #define PG8_WAIT_V(n) asm volatile("s_waitcnt vmcnt(" #n ")" ::: "memory")
; #define PG8_WAIT_L(n) asm volatile("s_waitcnt lgkmcnt(" #n ")" ::: "memory")
; #define PG8_BAR __builtin_amdgcn_s_barrier()
; #define PG8_SCHED __builtin_amdgcn_sched_barrier(0)
; template <class Epi, class Sched, bool ALIGN_EPI = false, bool SP2 = false>
; __device__ __forceinline__ void gemm_phase(PG8_LAS unsigned char* lds, const Gemm g, const Sched& S, const Epi& E) {
;     ...
;             PG8_WAIT_V(8); PG8_WAIT_L(0); PG8_BAR; PG8_MMA(1, 0, At, B0); PG8_MMA(1, 1, At, B1); PG8_BAR; PG8_SCHED;
;             PG8_LDB(B0, 1, 0); PG8_LDB(B1, 1, 1); PG8_SCHED; PG8_LDA(At, 1, 0); PG8_STAGE(PG8_SA(0, 1), a2 + hstep, voffA);
;             PG8_WAIT_V(8); PG8_WAIT_L(0); PG8_BAR; PG8_MMA(0, 0, At, B0); PG8_MMA(0, 1, At, B1); PG8_BAR; PG8_SCHED;
	s_setprio 1
	v_mfma_f32_16x16x32_bf16 v[58:61], v[142:145], v[180:183], v[58:61]
	v_mfma_f32_16x16x32_bf16 v[58:61], v[146:149], v[184:187], v[58:61]
	v_mfma_f32_16x16x32_bf16 v[42:45], v[146:149], v[192:195], v[42:45]
	v_mfma_f32_16x16x32_bf16 v[42:45], v[142:145], v[188:191], v[42:45]
	v_mfma_f32_16x16x32_bf16 v[26:29], v[142:145], v[202:205], v[26:29]
	v_mfma_f32_16x16x32_bf16 v[26:29], v[146:149], v[206:209], v[26:29]
	v_mfma_f32_16x16x32_bf16 v[10:13], v[146:149], v[214:217], v[10:13]
	v_mfma_f32_16x16x32_bf16 v[10:13], v[142:145], v[210:213], v[10:13]
	v_mfma_f32_16x16x32_bf16 v[62:65], v[150:153], v[180:183], v[62:65]
	v_mfma_f32_16x16x32_bf16 v[62:65], v[154:157], v[184:187], v[62:65]
	v_mfma_f32_16x16x32_bf16 v[46:49], v[154:157], v[192:195], v[46:49]
	v_mfma_f32_16x16x32_bf16 v[46:49], v[150:153], v[188:191], v[46:49]
	v_mfma_f32_16x16x32_bf16 v[30:33], v[150:153], v[202:205], v[30:33]
	v_mfma_f32_16x16x32_bf16 v[30:33], v[154:157], v[206:209], v[30:33]
	v_mfma_f32_16x16x32_bf16 v[14:17], v[154:157], v[214:217], v[14:17]
	v_mfma_f32_16x16x32_bf16 v[14:17], v[150:153], v[210:213], v[14:17]
	v_mfma_f32_16x16x32_bf16 v[50:53], v[158:161], v[180:183], v[50:53]
	v_mfma_f32_16x16x32_bf16 v[50:53], v[162:165], v[184:187], v[50:53]
	v_mfma_f32_16x16x32_bf16 v[34:37], v[162:165], v[192:195], v[34:37]
	v_mfma_f32_16x16x32_bf16 v[34:37], v[158:161], v[188:191], v[34:37]
	v_mfma_f32_16x16x32_bf16 v[18:21], v[158:161], v[202:205], v[18:21]
	v_mfma_f32_16x16x32_bf16 v[18:21], v[162:165], v[206:209], v[18:21]
	v_mfma_f32_16x16x32_bf16 v[2:5], v[162:165], v[214:217], v[2:5]
	v_mfma_f32_16x16x32_bf16 v[2:5], v[158:161], v[210:213], v[2:5]
	v_mfma_f32_16x16x32_bf16 v[54:57], v[172:175], v[180:183], v[54:57]
	v_mfma_f32_16x16x32_bf16 v[54:57], v[176:179], v[184:187], v[54:57]
	v_mfma_f32_16x16x32_bf16 v[38:41], v[176:179], v[192:195], v[38:41]
	v_mfma_f32_16x16x32_bf16 v[38:41], v[172:175], v[188:191], v[38:41]
	v_mfma_f32_16x16x32_bf16 v[22:25], v[172:175], v[202:205], v[22:25]
	v_mfma_f32_16x16x32_bf16 v[22:25], v[176:179], v[206:209], v[22:25]
	v_mfma_f32_16x16x32_bf16 v[6:9], v[176:179], v[214:217], v[6:9]
	v_mfma_f32_16x16x32_bf16 v[6:9], v[172:175], v[210:213], v[6:9]
	s_setprio 0
	s_barrier
	s_add_i32 s38, 0, 0x18000
	v_add_u32_e32 v0, s38, v167
	s_add_i32 s39, 0, 0x1c000
	ds_read_b128 v[142:145], v0
	ds_read_b128 v[146:149], v0 offset:1024
	ds_read_b128 v[150:153], v0 offset:2048
	ds_read_b128 v[154:157], v0 offset:3072
	v_add_u32_e32 v0, s39, v167
	ds_read_b128 v[158:161], v0
	ds_read_b128 v[162:165], v0 offset:1024
	ds_read_b128 v[172:175], v0 offset:2048
	ds_read_b128 v[176:179], v0 offset:3072
	s_add_u32 s72, s72, 0x40000
	s_addc_u32 s73, s73, 0
	s_mov_b32 m0, s78
	v_lshl_add_u64 v[226:227], s[72:73], 0, v[136:137]
	ds_read_b128 v[180:183], v170 offset:32768
	ds_read_b128 v[184:187], v170 offset:33792
	ds_read_b128 v[188:191], v170 offset:34816
	ds_read_b128 v[192:195], v170 offset:35840
	ds_read_b128 v[202:205], v170 offset:36864
	ds_read_b128 v[206:209], v170 offset:37888
	ds_read_b128 v[210:213], v170 offset:38912
	ds_read_b128 v[214:217], v170 offset:39936
	global_load_lds_dwordx4 v[226:227], off
	v_lshl_add_u64 v[226:227], s[72:73], 0, v[132:133]
	s_mov_b32 m0, s79
	s_nop 0
	global_load_lds_dwordx4 v[226:227], off
	s_waitcnt vmcnt(8)
	s_waitcnt lgkmcnt(0)
	s_barrier
	s_setprio 1
	v_mfma_f32_16x16x32_bf16 v[122:125], v[142:145], v[180:183], v[122:125]
	v_mfma_f32_16x16x32_bf16 v[122:125], v[146:149], v[184:187], v[122:125]
	v_mfma_f32_16x16x32_bf16 v[106:109], v[146:149], v[192:195], v[106:109]
	v_mfma_f32_16x16x32_bf16 v[106:109], v[142:145], v[188:191], v[106:109]
	v_mfma_f32_16x16x32_bf16 v[90:93], v[142:145], v[202:205], v[90:93]
	v_mfma_f32_16x16x32_bf16 v[90:93], v[146:149], v[206:209], v[90:93]
	v_mfma_f32_16x16x32_bf16 v[74:77], v[146:149], v[214:217], v[74:77]
	v_mfma_f32_16x16x32_bf16 v[74:77], v[142:145], v[210:213], v[74:77]
	v_mfma_f32_16x16x32_bf16 v[126:129], v[150:153], v[180:183], v[126:129]
	v_mfma_f32_16x16x32_bf16 v[126:129], v[154:157], v[184:187], v[126:129]
	v_mfma_f32_16x16x32_bf16 v[110:113], v[154:157], v[192:195], v[110:113]
	v_mfma_f32_16x16x32_bf16 v[110:113], v[150:153], v[188:191], v[110:113]
	v_mfma_f32_16x16x32_bf16 v[94:97], v[150:153], v[202:205], v[94:97]
	v_mfma_f32_16x16x32_bf16 v[94:97], v[154:157], v[206:209], v[94:97]
	v_mfma_f32_16x16x32_bf16 v[78:81], v[154:157], v[214:217], v[78:81]
	v_mfma_f32_16x16x32_bf16 v[78:81], v[150:153], v[210:213], v[78:81]
	v_mfma_f32_16x16x32_bf16 v[114:117], v[158:161], v[180:183], v[114:117]
	v_mfma_f32_16x16x32_bf16 v[114:117], v[162:165], v[184:187], v[114:117]
	v_mfma_f32_16x16x32_bf16 v[98:101], v[162:165], v[192:195], v[98:101]
	v_mfma_f32_16x16x32_bf16 v[98:101], v[158:161], v[188:191], v[98:101]
	v_mfma_f32_16x16x32_bf16 v[82:85], v[158:161], v[202:205], v[82:85]
	v_mfma_f32_16x16x32_bf16 v[82:85], v[162:165], v[206:209], v[82:85]
	v_mfma_f32_16x16x32_bf16 v[66:69], v[162:165], v[214:217], v[66:69]
	v_mfma_f32_16x16x32_bf16 v[66:69], v[158:161], v[210:213], v[66:69]
	v_mfma_f32_16x16x32_bf16 v[118:121], v[172:175], v[180:183], v[118:121]
	v_mfma_f32_16x16x32_bf16 v[118:121], v[176:179], v[184:187], v[118:121]
	v_mfma_f32_16x16x32_bf16 v[102:105], v[176:179], v[192:195], v[102:105]
	v_mfma_f32_16x16x32_bf16 v[102:105], v[172:175], v[188:191], v[102:105]
	v_mfma_f32_16x16x32_bf16 v[86:89], v[172:175], v[202:205], v[86:89]
	v_mfma_f32_16x16x32_bf16 v[86:89], v[176:179], v[206:209], v[86:89]
	v_mfma_f32_16x16x32_bf16 v[70:73], v[176:179], v[214:217], v[70:73]
	v_mfma_f32_16x16x32_bf16 v[70:73], v[172:175], v[210:213], v[70:73]
	s_setprio 0
	s_barrier
; #define PG8_STAGE(bufoff, gbase, voff) do { _Pragma("unroll") for (int _i = 0; _i < 2; ++_i) \
;         __builtin_amdgcn_global_load_lds((const unsigned*)((const char*)(gbase) + (voff)[_i]), (PG8_LAS unsigned*)(lds + (bufoff) + ldsw + _i * 8192), 16, 0, 0); } while (0)
; #define PG8_LDA(dst, b, h) do { _Pragma("unroll") for (int m = 0; m < 4; ++m) _Pragma("unroll") for (int k = 0; k < 2; ++k) dst[m][k] = *(const PG8_LAS bf16x8*)(lds + PG8_SA(b, h) + aoff + m * 2048 + k * 1024); } while (0)
; #define PG8_WAIT_V(n) asm volatile("s_waitcnt vmcnt(" #n ")" ::: "memory")
; template <class Epi, class Sched, bool ALIGN_EPI = false, bool SP2 = false>
; __device__ __forceinline__ void gemm_phase(PG8_LAS unsigned char* lds, const Gemm g, const Sched& S, const Epi& E) {
;     ...
;             PG8_LDA(At, 1, 1); PG8_STAGE(PG8_SB(1, 0), b3, voffB); PG8_STAGE(PG8_SB(1, 1), b3 + hstep, voffB); PG8_STAGE(PG8_SA(1, 0), a3, voffA);
;             PG8_WAIT_V(8); PG8_WAIT_L(0); PG8_BAR; PG8_MMA(1, 0, At, B0); PG8_MMA(1, 1, At, B1); PG8_BAR; PG8_SCHED;
;             } else {
;             PG8_LDB(B0, 0, 0); PG8_SCHED; PG8_LDA(At, 0, 0); PG8_STAGE(PG8_SA(1, 1), a1 + hstep, voffA);
;             PG8_WAIT_L(8); PG8_BAR; PG8_WAIT_L(0); PG8_MMA(0, 0, At, B0); PG8_BAR; PG8_SCHED;
;             PG8_LDB(B1, 0, 1); PG8_STAGE(PG8_SB(0, 0), b2, voffB);
;             PG8_BAR; PG8_WAIT_L(0); PG8_MMA(0, 1, At, B1); PG8_BAR;
;             PG8_LDA(At, 0, 1); PG8_STAGE(PG8_SA(0, 0), a2, voffA);
;             PG8_BAR; PG8_WAIT_L(0); PG8_MMA(1, 0, At, B0); PG8_BAR; PG8_SCHED;
;             PG8_STAGE(PG8_SB(0, 1), b2 + hstep, voffB);
;             PG8_WAIT_V(6); PG8_BAR; PG8_MMA(1, 1, At, B1); PG8_BAR;
;             PG8_LDB(B0, 1, 0); PG8_SCHED; PG8_LDA(At, 1, 0); PG8_STAGE(PG8_SA(0, 1), a2 + hstep, voffA);
;             PG8_WAIT_L(8); PG8_BAR; PG8_WAIT_L(0); PG8_MMA(0, 0, At, B0); PG8_BAR; PG8_SCHED;
;             PG8_LDB(B1, 1, 1); PG8_STAGE(PG8_SB(1, 0), b3, voffB);
;             PG8_BAR; PG8_WAIT_L(0); PG8_MMA(0, 1, At, B1); PG8_BAR;
;             PG8_LDA(At, 1, 1); PG8_STAGE(PG8_SA(1, 0), a3, voffA);
;             PG8_BAR; PG8_WAIT_L(0); PG8_MMA(1, 0, At, B0); PG8_BAR; PG8_SCHED;
;             PG8_STAGE(PG8_SB(1, 1), b3 + hstep, voffB);
;             PG8_WAIT_V(6); PG8_BAR; PG8_MMA(1, 1, At, B1); PG8_BAR;
;             }
;         }
;         if constexpr (ALIGN_EPI) { if (wr == 0) PG8_BAR; }
	s_add_i32 s38, s38, s75
	v_lshl_add_u64 v[218:219], v[218:219], 0, s[30:31]
	s_mov_b32 m0, s38
	ds_read_b128 v[180:183], v170 offset:49152
	ds_read_b128 v[184:187], v170 offset:50176
	ds_read_b128 v[188:191], v170 offset:51200
	ds_read_b128 v[192:195], v170 offset:52224
	ds_read_b128 v[202:205], v170 offset:53248
	ds_read_b128 v[206:209], v170 offset:54272
	ds_read_b128 v[210:213], v170 offset:55296
	ds_read_b128 v[214:217], v170 offset:56320
	global_load_lds_dwordx4 v[218:219], off
	s_add_i32 m0, s38, 0x2000
	s_add_u32 s46, s46, 0x40080
	v_lshl_add_u64 v[218:219], v[220:221], 0, s[30:31]
	s_addc_u32 s47, s47, 0
	s_add_i32 s38, s39, s75
	global_load_lds_dwordx4 v[218:219], off
	v_lshl_add_u64 v[218:219], s[46:47], 0, v[134:135]
	s_mov_b32 m0, s38
	s_nop 0
	global_load_lds_dwordx4 v[218:219], off
	v_lshl_add_u64 v[218:219], s[46:47], 0, v[130:131]
	s_add_i32 m0, s38, 0x2000
	s_nop 0
	global_load_lds_dwordx4 v[218:219], off
	v_lshl_add_u64 v[218:219], v[222:223], 0, s[30:31]
	s_mov_b32 m0, s80
	s_nop 0
	global_load_lds_dwordx4 v[218:219], off
	v_lshl_add_u64 v[218:219], v[224:225], 0, s[30:31]
	s_mov_b32 m0, s81
	s_nop 0
	global_load_lds_dwordx4 v[218:219], off
	s_waitcnt vmcnt(8)
	s_waitcnt lgkmcnt(0)
	s_barrier
	s_setprio 1
	v_mfma_f32_16x16x32_bf16 v[58:61], v[142:145], v[180:183], v[58:61]
	v_mfma_f32_16x16x32_bf16 v[58:61], v[146:149], v[184:187], v[58:61]
	v_mfma_f32_16x16x32_bf16 v[42:45], v[146:149], v[192:195], v[42:45]
	v_mfma_f32_16x16x32_bf16 v[42:45], v[142:145], v[188:191], v[42:45]
	v_mfma_f32_16x16x32_bf16 v[26:29], v[142:145], v[202:205], v[26:29]
	v_mfma_f32_16x16x32_bf16 v[26:29], v[146:149], v[206:209], v[26:29]
	v_mfma_f32_16x16x32_bf16 v[10:13], v[146:149], v[214:217], v[10:13]
	v_mfma_f32_16x16x32_bf16 v[10:13], v[142:145], v[210:213], v[10:13]
	v_mfma_f32_16x16x32_bf16 v[62:65], v[150:153], v[180:183], v[62:65]
	v_mfma_f32_16x16x32_bf16 v[62:65], v[154:157], v[184:187], v[62:65]
	v_mfma_f32_16x16x32_bf16 v[46:49], v[154:157], v[192:195], v[46:49]
	v_mfma_f32_16x16x32_bf16 v[46:49], v[150:153], v[188:191], v[46:49]
	v_mfma_f32_16x16x32_bf16 v[30:33], v[150:153], v[202:205], v[30:33]
	v_mfma_f32_16x16x32_bf16 v[30:33], v[154:157], v[206:209], v[30:33]
	v_mfma_f32_16x16x32_bf16 v[14:17], v[154:157], v[214:217], v[14:17]
	v_mfma_f32_16x16x32_bf16 v[14:17], v[150:153], v[210:213], v[14:17]
	v_mfma_f32_16x16x32_bf16 v[50:53], v[158:161], v[180:183], v[50:53]
	v_mfma_f32_16x16x32_bf16 v[50:53], v[162:165], v[184:187], v[50:53]
	v_mfma_f32_16x16x32_bf16 v[34:37], v[162:165], v[192:195], v[34:37]
	v_mfma_f32_16x16x32_bf16 v[34:37], v[158:161], v[188:191], v[34:37]
	v_mfma_f32_16x16x32_bf16 v[18:21], v[158:161], v[202:205], v[18:21]
	v_mfma_f32_16x16x32_bf16 v[18:21], v[162:165], v[206:209], v[18:21]
	v_mfma_f32_16x16x32_bf16 v[2:5], v[162:165], v[214:217], v[2:5]
	v_mfma_f32_16x16x32_bf16 v[2:5], v[158:161], v[210:213], v[2:5]
	v_mfma_f32_16x16x32_bf16 v[54:57], v[172:175], v[180:183], v[54:57]
	v_mfma_f32_16x16x32_bf16 v[54:57], v[176:179], v[184:187], v[54:57]
	v_mfma_f32_16x16x32_bf16 v[38:41], v[176:179], v[192:195], v[38:41]
	v_mfma_f32_16x16x32_bf16 v[38:41], v[172:175], v[188:191], v[38:41]
	v_mfma_f32_16x16x32_bf16 v[22:25], v[172:175], v[202:205], v[22:25]
	v_mfma_f32_16x16x32_bf16 v[22:25], v[176:179], v[206:209], v[22:25]
	v_mfma_f32_16x16x32_bf16 v[6:9], v[176:179], v[214:217], v[6:9]
	v_mfma_f32_16x16x32_bf16 v[6:9], v[172:175], v[210:213], v[6:9]
	s_setprio 0
	s_barrier
	s_add_i32 s84, s84, 2
	s_add_u32 s48, s48, 0x100
	s_addc_u32 s49, s49, 0
	s_add_u32 s53, s53, 0x100
	s_addc_u32 s69, s69, 0
	s_cmp_gt_u32 s84, 13
	s_cbranch_scc0 .LBB0_408
	s_and_b64 vcc, exec, s[64:65]
	s_cbranch_vccz .LBB0_411
	s_barrier
